# K-loops without any s_setprio (load segments carry no VALU any more), on top of group barriers
# speedup vs baseline: 1.0077x; 1.0056x over previous
.LBB0_350:
	s_add_u32 s46, s30, 0x1fc000
	s_addc_u32 s47, s31, 0
	s_and_b64 s[36:37], exec, s[36:37]
	s_cselect_b32 s46, s78, s46
	s_cselect_b32 s47, s19, s47
	s_add_u32 s36, s46, 0x200000
	s_addc_u32 s37, s47, 0
	s_add_i32 s79, 0, 0x10000
	s_add_i32 s86, 0, 0x14000
	ds_read_b128 v[148:151], v145
	ds_read_b128 v[152:155], v145 offset:1024
	ds_read_b128 v[156:159], v145 offset:2048
	ds_read_b128 v[160:163], v145 offset:3072
	ds_read_b128 v[164:167], v145 offset:16384
	ds_read_b128 v[168:171], v145 offset:17408
	ds_read_b128 v[172:175], v145 offset:18432
	ds_read_b128 v[176:179], v145 offset:19456
	s_add_i32 m0, s61, 0xc000
	ds_read_b128 v[180:183], v146
	ds_read_b128 v[184:187], v146 offset:1024
	ds_read_b128 v[188:191], v146 offset:2048
	ds_read_b128 v[192:195], v146 offset:3072
	ds_read_b128 v[200:203], v146 offset:4096
	ds_read_b128 v[204:207], v146 offset:5120
	ds_read_b128 v[208:211], v146 offset:6144
	ds_read_b128 v[222:225], v146 offset:7168
	global_load_lds_dwordx4 v140, s[30:31]
	s_add_i32 m0, s61, 0xe000
	s_nop 0
	global_load_lds_dwordx4 v142, s[30:31]
	s_waitcnt vmcnt(8)
	s_waitcnt lgkmcnt(0)
	s_barrier
	v_mfma_f32_16x16x32_bf16 v[128:131], v[148:151], v[180:183], v[128:131]
	v_mfma_f32_16x16x32_bf16 v[124:127], v[156:159], v[180:183], v[124:127]
	v_mfma_f32_16x16x32_bf16 v[112:115], v[148:151], v[188:191], v[112:115]
	v_mfma_f32_16x16x32_bf16 v[108:111], v[156:159], v[188:191], v[108:111]
	v_mfma_f32_16x16x32_bf16 v[96:99], v[148:151], v[200:203], v[96:99]
	v_mfma_f32_16x16x32_bf16 v[92:95], v[156:159], v[200:203], v[92:95]
	v_mfma_f32_16x16x32_bf16 v[80:83], v[148:151], v[208:211], v[80:83]
	v_mfma_f32_16x16x32_bf16 v[76:79], v[156:159], v[208:211], v[76:79]
	v_mfma_f32_16x16x32_bf16 v[128:131], v[152:155], v[184:187], v[128:131]
	v_mfma_f32_16x16x32_bf16 v[124:127], v[160:163], v[184:187], v[124:127]
	v_mfma_f32_16x16x32_bf16 v[112:115], v[152:155], v[192:195], v[112:115]
	v_mfma_f32_16x16x32_bf16 v[108:111], v[160:163], v[192:195], v[108:111]
	v_mfma_f32_16x16x32_bf16 v[96:99], v[152:155], v[204:207], v[96:99]
	v_mfma_f32_16x16x32_bf16 v[92:95], v[160:163], v[204:207], v[92:95]
	v_mfma_f32_16x16x32_bf16 v[80:83], v[152:155], v[222:225], v[80:83]
	v_mfma_f32_16x16x32_bf16 v[76:79], v[160:163], v[222:225], v[76:79]
	v_mfma_f32_16x16x32_bf16 v[120:123], v[164:167], v[180:183], v[120:123]
	v_mfma_f32_16x16x32_bf16 v[116:119], v[172:175], v[180:183], v[116:119]
	v_mfma_f32_16x16x32_bf16 v[104:107], v[164:167], v[188:191], v[104:107]
	v_mfma_f32_16x16x32_bf16 v[100:103], v[172:175], v[188:191], v[100:103]
	v_mfma_f32_16x16x32_bf16 v[88:91], v[164:167], v[200:203], v[88:91]
	v_mfma_f32_16x16x32_bf16 v[84:87], v[172:175], v[200:203], v[84:87]
	v_mfma_f32_16x16x32_bf16 v[72:75], v[164:167], v[208:211], v[72:75]
	v_mfma_f32_16x16x32_bf16 v[68:71], v[172:175], v[208:211], v[68:71]
	v_mfma_f32_16x16x32_bf16 v[120:123], v[168:171], v[184:187], v[120:123]
	v_mfma_f32_16x16x32_bf16 v[116:119], v[176:179], v[184:187], v[116:119]
	v_mfma_f32_16x16x32_bf16 v[104:107], v[168:171], v[192:195], v[104:107]
	v_mfma_f32_16x16x32_bf16 v[100:103], v[176:179], v[192:195], v[100:103]
	v_mfma_f32_16x16x32_bf16 v[88:91], v[168:171], v[204:207], v[88:91]
	v_mfma_f32_16x16x32_bf16 v[84:87], v[176:179], v[204:207], v[84:87]
	v_mfma_f32_16x16x32_bf16 v[72:75], v[168:171], v[222:225], v[72:75]
	v_mfma_f32_16x16x32_bf16 v[68:71], v[176:179], v[222:225], v[68:71]
	s_barrier
	s_add_i32 s79, s79, s58
	s_mov_b32 m0, s79
	ds_read_b128 v[180:183], v146 offset:16384
	ds_read_b128 v[184:187], v146 offset:17408
	ds_read_b128 v[188:191], v146 offset:18432
	ds_read_b128 v[192:195], v146 offset:19456
	ds_read_b128 v[200:203], v146 offset:20480
	ds_read_b128 v[204:207], v146 offset:21504
	ds_read_b128 v[208:211], v146 offset:22528
	ds_read_b128 v[222:225], v146 offset:23552
	global_load_lds_dwordx4 v136, s[44:45]
	s_add_i32 m0, s79, 0x2000
	s_add_u32 s82, s44, 0x4000
	s_addc_u32 s83, s45, 0
	s_add_i32 s79, s86, s58
	global_load_lds_dwordx4 v132, s[44:45]
	s_mov_b32 m0, s79
	s_nop 0
	global_load_lds_dwordx4 v136, s[82:83]
	s_add_i32 m0, s79, 0x2000
	s_nop 0
	global_load_lds_dwordx4 v132, s[82:83]
	s_mov_b32 m0, s61
	s_nop 0
	global_load_lds_dwordx4 v138, s[46:47]
	s_mov_b32 m0, s66
	s_nop 0
	global_load_lds_dwordx4 v134, s[46:47]
	s_waitcnt vmcnt(8)
	s_waitcnt lgkmcnt(0)
	s_barrier
	v_mfma_f32_16x16x32_bf16 v[64:67], v[148:151], v[180:183], v[64:67]
	v_mfma_f32_16x16x32_bf16 v[60:63], v[156:159], v[180:183], v[60:63]
	v_mfma_f32_16x16x32_bf16 v[48:51], v[148:151], v[188:191], v[48:51]
	v_mfma_f32_16x16x32_bf16 v[44:47], v[156:159], v[188:191], v[44:47]
	v_mfma_f32_16x16x32_bf16 v[32:35], v[148:151], v[200:203], v[32:35]
	v_mfma_f32_16x16x32_bf16 v[28:31], v[156:159], v[200:203], v[28:31]
	v_mfma_f32_16x16x32_bf16 v[12:15], v[148:151], v[208:211], v[12:15]
	v_mfma_f32_16x16x32_bf16 v[16:19], v[156:159], v[208:211], v[16:19]
	v_mfma_f32_16x16x32_bf16 v[64:67], v[152:155], v[184:187], v[64:67]
	v_mfma_f32_16x16x32_bf16 v[60:63], v[160:163], v[184:187], v[60:63]
	v_mfma_f32_16x16x32_bf16 v[48:51], v[152:155], v[192:195], v[48:51]
	v_mfma_f32_16x16x32_bf16 v[44:47], v[160:163], v[192:195], v[44:47]
	v_mfma_f32_16x16x32_bf16 v[32:35], v[152:155], v[204:207], v[32:35]
	v_mfma_f32_16x16x32_bf16 v[28:31], v[160:163], v[204:207], v[28:31]
	v_mfma_f32_16x16x32_bf16 v[12:15], v[152:155], v[222:225], v[12:15]
	v_mfma_f32_16x16x32_bf16 v[16:19], v[160:163], v[222:225], v[16:19]
	v_mfma_f32_16x16x32_bf16 v[56:59], v[164:167], v[180:183], v[56:59]
	v_mfma_f32_16x16x32_bf16 v[52:55], v[172:175], v[180:183], v[52:55]
	v_mfma_f32_16x16x32_bf16 v[40:43], v[164:167], v[188:191], v[40:43]
	v_mfma_f32_16x16x32_bf16 v[36:39], v[172:175], v[188:191], v[36:39]
	v_mfma_f32_16x16x32_bf16 v[24:27], v[164:167], v[200:203], v[24:27]
	v_mfma_f32_16x16x32_bf16 v[20:23], v[172:175], v[200:203], v[20:23]
	v_mfma_f32_16x16x32_bf16 v[4:7], v[164:167], v[208:211], v[4:7]
	v_mfma_f32_16x16x32_bf16 v[8:11], v[172:175], v[208:211], v[8:11]
	v_mfma_f32_16x16x32_bf16 v[56:59], v[168:171], v[184:187], v[56:59]
	v_mfma_f32_16x16x32_bf16 v[52:55], v[176:179], v[184:187], v[52:55]
	v_mfma_f32_16x16x32_bf16 v[40:43], v[168:171], v[192:195], v[40:43]
	v_mfma_f32_16x16x32_bf16 v[36:39], v[176:179], v[192:195], v[36:39]
	v_mfma_f32_16x16x32_bf16 v[24:27], v[168:171], v[204:207], v[24:27]
	v_mfma_f32_16x16x32_bf16 v[20:23], v[176:179], v[204:207], v[20:23]
	v_mfma_f32_16x16x32_bf16 v[4:7], v[168:171], v[222:225], v[4:7]
	v_mfma_f32_16x16x32_bf16 v[8:11], v[176:179], v[222:225], v[8:11]
	s_barrier
	s_add_i32 s79, 0, 0x18000
	s_add_i32 s82, 0, 0x1c000
	ds_read_b128 v[148:151], v145 offset:32768
	ds_read_b128 v[152:155], v145 offset:33792
	ds_read_b128 v[156:159], v145 offset:34816
	ds_read_b128 v[160:163], v145 offset:35840
	ds_read_b128 v[164:167], v145 offset:49152
	ds_read_b128 v[168:171], v145 offset:50176
	ds_read_b128 v[172:175], v145 offset:51200
	ds_read_b128 v[176:179], v145 offset:52224
	s_add_u32 s46, s46, 0x4000
	s_addc_u32 s47, s47, 0
	s_mov_b32 m0, s67
	ds_read_b128 v[180:183], v146 offset:32768
	ds_read_b128 v[184:187], v146 offset:33792
	ds_read_b128 v[188:191], v146 offset:34816
	ds_read_b128 v[192:195], v146 offset:35840
	ds_read_b128 v[200:203], v146 offset:36864
	ds_read_b128 v[204:207], v146 offset:37888
	ds_read_b128 v[208:211], v146 offset:38912
	ds_read_b128 v[222:225], v146 offset:39936
	global_load_lds_dwordx4 v138, s[46:47]
	s_mov_b32 m0, s70
	s_nop 0
	global_load_lds_dwordx4 v134, s[46:47]
	s_waitcnt vmcnt(8)
	s_waitcnt lgkmcnt(0)
	s_barrier
	v_mfma_f32_16x16x32_bf16 v[128:131], v[148:151], v[180:183], v[128:131]
	v_mfma_f32_16x16x32_bf16 v[124:127], v[156:159], v[180:183], v[124:127]
	v_mfma_f32_16x16x32_bf16 v[112:115], v[148:151], v[188:191], v[112:115]
	v_mfma_f32_16x16x32_bf16 v[108:111], v[156:159], v[188:191], v[108:111]
	v_mfma_f32_16x16x32_bf16 v[96:99], v[148:151], v[200:203], v[96:99]
	v_mfma_f32_16x16x32_bf16 v[92:95], v[156:159], v[200:203], v[92:95]
	v_mfma_f32_16x16x32_bf16 v[80:83], v[148:151], v[208:211], v[80:83]
	v_mfma_f32_16x16x32_bf16 v[76:79], v[156:159], v[208:211], v[76:79]
	v_mfma_f32_16x16x32_bf16 v[128:131], v[152:155], v[184:187], v[128:131]
	v_mfma_f32_16x16x32_bf16 v[124:127], v[160:163], v[184:187], v[124:127]
	v_mfma_f32_16x16x32_bf16 v[112:115], v[152:155], v[192:195], v[112:115]
	v_mfma_f32_16x16x32_bf16 v[108:111], v[160:163], v[192:195], v[108:111]
	v_mfma_f32_16x16x32_bf16 v[96:99], v[152:155], v[204:207], v[96:99]
	v_mfma_f32_16x16x32_bf16 v[92:95], v[160:163], v[204:207], v[92:95]
	v_mfma_f32_16x16x32_bf16 v[80:83], v[152:155], v[222:225], v[80:83]
	v_mfma_f32_16x16x32_bf16 v[76:79], v[160:163], v[222:225], v[76:79]
	v_mfma_f32_16x16x32_bf16 v[120:123], v[164:167], v[180:183], v[120:123]
	v_mfma_f32_16x16x32_bf16 v[116:119], v[172:175], v[180:183], v[116:119]
	v_mfma_f32_16x16x32_bf16 v[104:107], v[164:167], v[188:191], v[104:107]
	v_mfma_f32_16x16x32_bf16 v[100:103], v[172:175], v[188:191], v[100:103]
	v_mfma_f32_16x16x32_bf16 v[88:91], v[164:167], v[200:203], v[88:91]
	v_mfma_f32_16x16x32_bf16 v[84:87], v[172:175], v[200:203], v[84:87]
	v_mfma_f32_16x16x32_bf16 v[72:75], v[164:167], v[208:211], v[72:75]
	v_mfma_f32_16x16x32_bf16 v[68:71], v[172:175], v[208:211], v[68:71]
	v_mfma_f32_16x16x32_bf16 v[120:123], v[168:171], v[184:187], v[120:123]
	v_mfma_f32_16x16x32_bf16 v[116:119], v[176:179], v[184:187], v[116:119]
	v_mfma_f32_16x16x32_bf16 v[104:107], v[168:171], v[192:195], v[104:107]
	v_mfma_f32_16x16x32_bf16 v[100:103], v[176:179], v[192:195], v[100:103]
	v_mfma_f32_16x16x32_bf16 v[88:91], v[168:171], v[204:207], v[88:91]
	v_mfma_f32_16x16x32_bf16 v[84:87], v[176:179], v[204:207], v[84:87]
	v_mfma_f32_16x16x32_bf16 v[72:75], v[168:171], v[222:225], v[72:75]
	v_mfma_f32_16x16x32_bf16 v[68:71], v[176:179], v[222:225], v[68:71]
	s_barrier
	s_add_u32 s46, s44, 0x160000
	s_addc_u32 s47, s45, 0
	s_add_i32 s79, s79, s58
	s_mov_b32 m0, s79
	ds_read_b128 v[180:183], v146 offset:49152
	ds_read_b128 v[184:187], v146 offset:50176
	ds_read_b128 v[188:191], v146 offset:51200
	ds_read_b128 v[192:195], v146 offset:52224
	ds_read_b128 v[200:203], v146 offset:53248
	ds_read_b128 v[204:207], v146 offset:54272
	ds_read_b128 v[208:211], v146 offset:55296
	ds_read_b128 v[222:225], v146 offset:56320
	global_load_lds_dwordx4 v136, s[46:47]
	s_add_i32 m0, s79, 0x2000
	s_add_u32 s44, s44, 0x164000
	s_addc_u32 s45, s45, 0
	global_load_lds_dwordx4 v132, s[46:47]
	s_add_i32 s46, s82, s58
	s_mov_b32 m0, s46
	s_nop 0
	global_load_lds_dwordx4 v136, s[44:45]
	s_add_i32 m0, s46, 0x2000
	s_nop 0
	global_load_lds_dwordx4 v132, s[44:45]
	s_mov_b32 m0, s75
	s_nop 0
	global_load_lds_dwordx4 v138, s[36:37]
	s_mov_b32 m0, s76
	s_nop 0
	global_load_lds_dwordx4 v134, s[36:37]
	s_waitcnt vmcnt(8)
	s_waitcnt lgkmcnt(0)
	s_barrier
	v_mfma_f32_16x16x32_bf16 v[64:67], v[148:151], v[180:183], v[64:67]
	v_mfma_f32_16x16x32_bf16 v[60:63], v[156:159], v[180:183], v[60:63]
	v_mfma_f32_16x16x32_bf16 v[48:51], v[148:151], v[188:191], v[48:51]
	v_mfma_f32_16x16x32_bf16 v[44:47], v[156:159], v[188:191], v[44:47]
	v_mfma_f32_16x16x32_bf16 v[32:35], v[148:151], v[200:203], v[32:35]
	v_mfma_f32_16x16x32_bf16 v[28:31], v[156:159], v[200:203], v[28:31]
	v_mfma_f32_16x16x32_bf16 v[12:15], v[148:151], v[208:211], v[12:15]
	v_mfma_f32_16x16x32_bf16 v[16:19], v[156:159], v[208:211], v[16:19]
	v_mfma_f32_16x16x32_bf16 v[64:67], v[152:155], v[184:187], v[64:67]
	v_mfma_f32_16x16x32_bf16 v[60:63], v[160:163], v[184:187], v[60:63]
	v_mfma_f32_16x16x32_bf16 v[48:51], v[152:155], v[192:195], v[48:51]
	v_mfma_f32_16x16x32_bf16 v[44:47], v[160:163], v[192:195], v[44:47]
	v_mfma_f32_16x16x32_bf16 v[32:35], v[152:155], v[204:207], v[32:35]
	v_mfma_f32_16x16x32_bf16 v[28:31], v[160:163], v[204:207], v[28:31]
	v_mfma_f32_16x16x32_bf16 v[12:15], v[152:155], v[222:225], v[12:15]
	v_mfma_f32_16x16x32_bf16 v[16:19], v[160:163], v[222:225], v[16:19]
	v_mfma_f32_16x16x32_bf16 v[56:59], v[164:167], v[180:183], v[56:59]
	v_mfma_f32_16x16x32_bf16 v[52:55], v[172:175], v[180:183], v[52:55]
	v_mfma_f32_16x16x32_bf16 v[40:43], v[164:167], v[188:191], v[40:43]
	v_mfma_f32_16x16x32_bf16 v[36:39], v[172:175], v[188:191], v[36:39]
	v_mfma_f32_16x16x32_bf16 v[24:27], v[164:167], v[200:203], v[24:27]
	v_mfma_f32_16x16x32_bf16 v[20:23], v[172:175], v[200:203], v[20:23]
	v_mfma_f32_16x16x32_bf16 v[4:7], v[164:167], v[208:211], v[4:7]
	v_mfma_f32_16x16x32_bf16 v[8:11], v[172:175], v[208:211], v[8:11]
	v_mfma_f32_16x16x32_bf16 v[56:59], v[168:171], v[184:187], v[56:59]
	v_mfma_f32_16x16x32_bf16 v[52:55], v[176:179], v[184:187], v[52:55]
	v_mfma_f32_16x16x32_bf16 v[40:43], v[168:171], v[192:195], v[40:43]
	v_mfma_f32_16x16x32_bf16 v[36:39], v[176:179], v[192:195], v[36:39]
	v_mfma_f32_16x16x32_bf16 v[24:27], v[168:171], v[204:207], v[24:27]
	v_mfma_f32_16x16x32_bf16 v[20:23], v[176:179], v[204:207], v[20:23]
	v_mfma_f32_16x16x32_bf16 v[4:7], v[168:171], v[222:225], v[4:7]
	v_mfma_f32_16x16x32_bf16 v[8:11], v[176:179], v[222:225], v[8:11]
	s_barrier
	s_add_i32 s15, s15, 2
	s_add_u32 s28, s28, 0x2c0000
	s_addc_u32 s29, s29, 0
	s_add_u32 s30, s30, 0x400000
	s_addc_u32 s31, s31, 0
	s_cmp_gt_u32 s15, 29
	s_cbranch_scc1 .LBB0_353

.LBB0_433:
	s_add_u32 s30, s28, 0x1fc000
	s_addc_u32 s31, s29, 0
	s_cmpk_eq_i32 s58, 0x54
	s_cselect_b32 s44, s34, s30
	s_cselect_b32 s45, s21, s31
	s_cselect_b32 s37, s19, s49
	s_cselect_b32 s36, s35, s48
	s_add_u32 s30, s44, 0x200000
	s_addc_u32 s31, s45, 0
	s_add_i32 s59, 0, 0x10000
	s_add_i32 s61, 0, 0x14000
	ds_read_b128 v[132:135], v203
	ds_read_b128 v[136:139], v203 offset:1024
	ds_read_b128 v[140:143], v203 offset:2048
	ds_read_b128 v[144:147], v203 offset:3072
	ds_read_b128 v[148:151], v203 offset:16384
	ds_read_b128 v[152:155], v203 offset:17408
	ds_read_b128 v[156:159], v203 offset:18432
	ds_read_b128 v[170:173], v203 offset:19456
	s_add_i32 m0, s76, 0xc000
	ds_read_b128 v[174:177], v205
	ds_read_b128 v[178:181], v205 offset:1024
	ds_read_b128 v[182:185], v205 offset:2048
	ds_read_b128 v[186:189], v205 offset:3072
	ds_read_b128 v[190:193], v205 offset:4096
	ds_read_b128 v[206:209], v205 offset:5120
	ds_read_b128 v[210:213], v205 offset:6144
	ds_read_b128 v[222:225], v205 offset:7168
	global_load_lds_dwordx4 v166, s[28:29]
	s_add_i32 m0, s76, 0xe000
	s_nop 0
	global_load_lds_dwordx4 v168, s[28:29]
	s_waitcnt vmcnt(8)
	s_waitcnt lgkmcnt(0)
	s_barrier
	v_mfma_f32_16x16x32_bf16 v[128:131], v[132:135], v[174:177], v[128:131]
	v_mfma_f32_16x16x32_bf16 v[124:127], v[140:143], v[174:177], v[124:127]
	v_mfma_f32_16x16x32_bf16 v[112:115], v[132:135], v[182:185], v[112:115]
	v_mfma_f32_16x16x32_bf16 v[108:111], v[140:143], v[182:185], v[108:111]
	v_mfma_f32_16x16x32_bf16 v[96:99], v[132:135], v[190:193], v[96:99]
	v_mfma_f32_16x16x32_bf16 v[92:95], v[140:143], v[190:193], v[92:95]
	v_mfma_f32_16x16x32_bf16 v[88:91], v[132:135], v[210:213], v[88:91]
	v_mfma_f32_16x16x32_bf16 v[80:83], v[140:143], v[210:213], v[80:83]
	v_mfma_f32_16x16x32_bf16 v[128:131], v[136:139], v[178:181], v[128:131]
	v_mfma_f32_16x16x32_bf16 v[124:127], v[144:147], v[178:181], v[124:127]
	v_mfma_f32_16x16x32_bf16 v[112:115], v[136:139], v[186:189], v[112:115]
	v_mfma_f32_16x16x32_bf16 v[108:111], v[144:147], v[186:189], v[108:111]
	v_mfma_f32_16x16x32_bf16 v[96:99], v[136:139], v[206:209], v[96:99]
	v_mfma_f32_16x16x32_bf16 v[92:95], v[144:147], v[206:209], v[92:95]
	v_mfma_f32_16x16x32_bf16 v[88:91], v[136:139], v[222:225], v[88:91]
	v_mfma_f32_16x16x32_bf16 v[80:83], v[144:147], v[222:225], v[80:83]
	v_mfma_f32_16x16x32_bf16 v[120:123], v[148:151], v[174:177], v[120:123]
	v_mfma_f32_16x16x32_bf16 v[116:119], v[156:159], v[174:177], v[116:119]
	v_mfma_f32_16x16x32_bf16 v[104:107], v[148:151], v[182:185], v[104:107]
	v_mfma_f32_16x16x32_bf16 v[100:103], v[156:159], v[182:185], v[100:103]
	v_mfma_f32_16x16x32_bf16 v[84:87], v[148:151], v[190:193], v[84:87]
	v_mfma_f32_16x16x32_bf16 v[76:79], v[156:159], v[190:193], v[76:79]
	v_mfma_f32_16x16x32_bf16 v[72:75], v[148:151], v[210:213], v[72:75]
	v_mfma_f32_16x16x32_bf16 v[68:71], v[156:159], v[210:213], v[68:71]
	v_mfma_f32_16x16x32_bf16 v[120:123], v[152:155], v[178:181], v[120:123]
	v_mfma_f32_16x16x32_bf16 v[116:119], v[170:173], v[178:181], v[116:119]
	v_mfma_f32_16x16x32_bf16 v[104:107], v[152:155], v[186:189], v[104:107]
	v_mfma_f32_16x16x32_bf16 v[100:103], v[170:173], v[186:189], v[100:103]
	v_mfma_f32_16x16x32_bf16 v[84:87], v[152:155], v[206:209], v[84:87]
	v_mfma_f32_16x16x32_bf16 v[76:79], v[170:173], v[206:209], v[76:79]
	v_mfma_f32_16x16x32_bf16 v[72:75], v[152:155], v[222:225], v[72:75]
	v_mfma_f32_16x16x32_bf16 v[68:71], v[170:173], v[222:225], v[68:71]
	s_barrier
	s_add_i32 s59, s59, s75
	s_mov_b32 m0, s59
	ds_read_b128 v[174:177], v205 offset:16384
	ds_read_b128 v[178:181], v205 offset:17408
	ds_read_b128 v[182:185], v205 offset:18432
	ds_read_b128 v[186:189], v205 offset:19456
	ds_read_b128 v[190:193], v205 offset:20480
	ds_read_b128 v[206:209], v205 offset:21504
	ds_read_b128 v[210:213], v205 offset:22528
	ds_read_b128 v[222:225], v205 offset:23552
	global_load_lds_dwordx4 v2, s[36:37]
	s_add_i32 m0, s59, 0x2000
	s_add_u32 s66, s36, 0x4000
	s_addc_u32 s67, s37, 0
	s_add_i32 s59, s61, s75
	global_load_lds_dwordx4 v164, s[36:37]
	s_mov_b32 m0, s59
	s_nop 0
	global_load_lds_dwordx4 v2, s[66:67]
	s_add_i32 m0, s59, 0x2000
	s_nop 0
	global_load_lds_dwordx4 v164, s[66:67]
	s_mov_b32 m0, s76
	s_nop 0
	global_load_lds_dwordx4 v160, s[44:45]
	s_mov_b32 m0, s77
	s_nop 0
	global_load_lds_dwordx4 v162, s[44:45]
	s_waitcnt vmcnt(8)
	s_waitcnt lgkmcnt(0)
	s_barrier
	v_mfma_f32_16x16x32_bf16 v[64:67], v[132:135], v[174:177], v[64:67]
	v_mfma_f32_16x16x32_bf16 v[60:63], v[140:143], v[174:177], v[60:63]
	v_mfma_f32_16x16x32_bf16 v[48:51], v[132:135], v[182:185], v[48:51]
	v_mfma_f32_16x16x32_bf16 v[44:47], v[140:143], v[182:185], v[44:47]
	v_mfma_f32_16x16x32_bf16 v[32:35], v[132:135], v[190:193], v[32:35]
	v_mfma_f32_16x16x32_bf16 v[28:31], v[140:143], v[190:193], v[28:31]
	v_mfma_f32_16x16x32_bf16 v[16:19], v[132:135], v[210:213], v[16:19]
	v_mfma_f32_16x16x32_bf16 v[12:15], v[140:143], v[210:213], v[12:15]
	v_mfma_f32_16x16x32_bf16 v[64:67], v[136:139], v[178:181], v[64:67]
	v_mfma_f32_16x16x32_bf16 v[60:63], v[144:147], v[178:181], v[60:63]
	v_mfma_f32_16x16x32_bf16 v[48:51], v[136:139], v[186:189], v[48:51]
	v_mfma_f32_16x16x32_bf16 v[44:47], v[144:147], v[186:189], v[44:47]
	v_mfma_f32_16x16x32_bf16 v[32:35], v[136:139], v[206:209], v[32:35]
	v_mfma_f32_16x16x32_bf16 v[28:31], v[144:147], v[206:209], v[28:31]
	v_mfma_f32_16x16x32_bf16 v[16:19], v[136:139], v[222:225], v[16:19]
	v_mfma_f32_16x16x32_bf16 v[12:15], v[144:147], v[222:225], v[12:15]
	v_mfma_f32_16x16x32_bf16 v[56:59], v[148:151], v[174:177], v[56:59]
	v_mfma_f32_16x16x32_bf16 v[52:55], v[156:159], v[174:177], v[52:55]
	v_mfma_f32_16x16x32_bf16 v[40:43], v[148:151], v[182:185], v[40:43]
	v_mfma_f32_16x16x32_bf16 v[36:39], v[156:159], v[182:185], v[36:39]
	v_mfma_f32_16x16x32_bf16 v[24:27], v[148:151], v[190:193], v[24:27]
	v_mfma_f32_16x16x32_bf16 v[20:23], v[156:159], v[190:193], v[20:23]
	v_mfma_f32_16x16x32_bf16 v[8:11], v[148:151], v[210:213], v[8:11]
	v_mfma_f32_16x16x32_bf16 v[4:7], v[156:159], v[210:213], v[4:7]
	v_mfma_f32_16x16x32_bf16 v[56:59], v[152:155], v[178:181], v[56:59]
	v_mfma_f32_16x16x32_bf16 v[52:55], v[170:173], v[178:181], v[52:55]
	v_mfma_f32_16x16x32_bf16 v[40:43], v[152:155], v[186:189], v[40:43]
	v_mfma_f32_16x16x32_bf16 v[36:39], v[170:173], v[186:189], v[36:39]
	v_mfma_f32_16x16x32_bf16 v[24:27], v[152:155], v[206:209], v[24:27]
	v_mfma_f32_16x16x32_bf16 v[20:23], v[170:173], v[206:209], v[20:23]
	v_mfma_f32_16x16x32_bf16 v[8:11], v[152:155], v[222:225], v[8:11]
	v_mfma_f32_16x16x32_bf16 v[4:7], v[170:173], v[222:225], v[4:7]
	s_barrier
	s_add_i32 s59, 0, 0x18000
	s_add_i32 s61, 0, 0x1c000
	ds_read_b128 v[132:135], v203 offset:32768
	ds_read_b128 v[136:139], v203 offset:33792
	ds_read_b128 v[140:143], v203 offset:34816
	ds_read_b128 v[144:147], v203 offset:35840
	ds_read_b128 v[148:151], v203 offset:49152
	ds_read_b128 v[152:155], v203 offset:50176
	ds_read_b128 v[156:159], v203 offset:51200
	ds_read_b128 v[170:173], v203 offset:52224
	s_add_u32 s44, s44, 0x4000
	s_addc_u32 s45, s45, 0
	s_mov_b32 m0, s78
	ds_read_b128 v[174:177], v205 offset:32768
	ds_read_b128 v[178:181], v205 offset:33792
	ds_read_b128 v[182:185], v205 offset:34816
	ds_read_b128 v[186:189], v205 offset:35840
	ds_read_b128 v[190:193], v205 offset:36864
	ds_read_b128 v[206:209], v205 offset:37888
	ds_read_b128 v[210:213], v205 offset:38912
	ds_read_b128 v[222:225], v205 offset:39936
	global_load_lds_dwordx4 v160, s[44:45]
	s_mov_b32 m0, s79
	s_nop 0
	global_load_lds_dwordx4 v162, s[44:45]
	s_waitcnt vmcnt(8)
	s_waitcnt lgkmcnt(0)
	s_barrier
	v_mfma_f32_16x16x32_bf16 v[128:131], v[132:135], v[174:177], v[128:131]
	v_mfma_f32_16x16x32_bf16 v[124:127], v[140:143], v[174:177], v[124:127]
	v_mfma_f32_16x16x32_bf16 v[112:115], v[132:135], v[182:185], v[112:115]
	v_mfma_f32_16x16x32_bf16 v[108:111], v[140:143], v[182:185], v[108:111]
	v_mfma_f32_16x16x32_bf16 v[96:99], v[132:135], v[190:193], v[96:99]
	v_mfma_f32_16x16x32_bf16 v[92:95], v[140:143], v[190:193], v[92:95]
	v_mfma_f32_16x16x32_bf16 v[88:91], v[132:135], v[210:213], v[88:91]
	v_mfma_f32_16x16x32_bf16 v[80:83], v[140:143], v[210:213], v[80:83]
	v_mfma_f32_16x16x32_bf16 v[128:131], v[136:139], v[178:181], v[128:131]
	v_mfma_f32_16x16x32_bf16 v[124:127], v[144:147], v[178:181], v[124:127]
	v_mfma_f32_16x16x32_bf16 v[112:115], v[136:139], v[186:189], v[112:115]
	v_mfma_f32_16x16x32_bf16 v[108:111], v[144:147], v[186:189], v[108:111]
	v_mfma_f32_16x16x32_bf16 v[96:99], v[136:139], v[206:209], v[96:99]
	v_mfma_f32_16x16x32_bf16 v[92:95], v[144:147], v[206:209], v[92:95]
	v_mfma_f32_16x16x32_bf16 v[88:91], v[136:139], v[222:225], v[88:91]
	v_mfma_f32_16x16x32_bf16 v[80:83], v[144:147], v[222:225], v[80:83]
	v_mfma_f32_16x16x32_bf16 v[120:123], v[148:151], v[174:177], v[120:123]
	v_mfma_f32_16x16x32_bf16 v[116:119], v[156:159], v[174:177], v[116:119]
	v_mfma_f32_16x16x32_bf16 v[104:107], v[148:151], v[182:185], v[104:107]
	v_mfma_f32_16x16x32_bf16 v[100:103], v[156:159], v[182:185], v[100:103]
	v_mfma_f32_16x16x32_bf16 v[84:87], v[148:151], v[190:193], v[84:87]
	v_mfma_f32_16x16x32_bf16 v[76:79], v[156:159], v[190:193], v[76:79]
	v_mfma_f32_16x16x32_bf16 v[72:75], v[148:151], v[210:213], v[72:75]
	v_mfma_f32_16x16x32_bf16 v[68:71], v[156:159], v[210:213], v[68:71]
	v_mfma_f32_16x16x32_bf16 v[120:123], v[152:155], v[178:181], v[120:123]
	v_mfma_f32_16x16x32_bf16 v[116:119], v[170:173], v[178:181], v[116:119]
	v_mfma_f32_16x16x32_bf16 v[104:107], v[152:155], v[186:189], v[104:107]
	v_mfma_f32_16x16x32_bf16 v[100:103], v[170:173], v[186:189], v[100:103]
	v_mfma_f32_16x16x32_bf16 v[84:87], v[152:155], v[206:209], v[84:87]
	v_mfma_f32_16x16x32_bf16 v[76:79], v[170:173], v[206:209], v[76:79]
	v_mfma_f32_16x16x32_bf16 v[72:75], v[152:155], v[222:225], v[72:75]
	v_mfma_f32_16x16x32_bf16 v[68:71], v[170:173], v[222:225], v[68:71]
	s_barrier
	s_add_u32 s44, s36, 0x40000
	s_addc_u32 s45, s37, 0
	s_add_i32 s59, s59, s75
	s_mov_b32 m0, s59
	ds_read_b128 v[174:177], v205 offset:49152
	ds_read_b128 v[178:181], v205 offset:50176
	ds_read_b128 v[182:185], v205 offset:51200
	ds_read_b128 v[186:189], v205 offset:52224
	ds_read_b128 v[190:193], v205 offset:53248
	ds_read_b128 v[206:209], v205 offset:54272
	ds_read_b128 v[210:213], v205 offset:55296
	ds_read_b128 v[222:225], v205 offset:56320
	global_load_lds_dwordx4 v2, s[44:45]
	s_add_i32 m0, s59, 0x2000
	s_add_u32 s36, s36, 0x44000
	s_addc_u32 s37, s37, 0
	global_load_lds_dwordx4 v164, s[44:45]
	s_add_i32 s44, s61, s75
	s_mov_b32 m0, s44
	s_nop 0
	global_load_lds_dwordx4 v2, s[36:37]
	s_add_i32 m0, s44, 0x2000
	s_nop 0
	global_load_lds_dwordx4 v164, s[36:37]
	s_mov_b32 m0, s82
	s_nop 0
	global_load_lds_dwordx4 v160, s[30:31]
	s_mov_b32 m0, s83
	s_nop 0
	global_load_lds_dwordx4 v162, s[30:31]
	s_waitcnt vmcnt(8)
	s_waitcnt lgkmcnt(0)
	s_barrier
	v_mfma_f32_16x16x32_bf16 v[64:67], v[132:135], v[174:177], v[64:67]
	v_mfma_f32_16x16x32_bf16 v[60:63], v[140:143], v[174:177], v[60:63]
	v_mfma_f32_16x16x32_bf16 v[48:51], v[132:135], v[182:185], v[48:51]
	v_mfma_f32_16x16x32_bf16 v[44:47], v[140:143], v[182:185], v[44:47]
	v_mfma_f32_16x16x32_bf16 v[32:35], v[132:135], v[190:193], v[32:35]
	v_mfma_f32_16x16x32_bf16 v[28:31], v[140:143], v[190:193], v[28:31]
	v_mfma_f32_16x16x32_bf16 v[16:19], v[132:135], v[210:213], v[16:19]
	v_mfma_f32_16x16x32_bf16 v[12:15], v[140:143], v[210:213], v[12:15]
	v_mfma_f32_16x16x32_bf16 v[64:67], v[136:139], v[178:181], v[64:67]
	v_mfma_f32_16x16x32_bf16 v[60:63], v[144:147], v[178:181], v[60:63]
	v_mfma_f32_16x16x32_bf16 v[48:51], v[136:139], v[186:189], v[48:51]
	v_mfma_f32_16x16x32_bf16 v[44:47], v[144:147], v[186:189], v[44:47]
	v_mfma_f32_16x16x32_bf16 v[32:35], v[136:139], v[206:209], v[32:35]
	v_mfma_f32_16x16x32_bf16 v[28:31], v[144:147], v[206:209], v[28:31]
	v_mfma_f32_16x16x32_bf16 v[16:19], v[136:139], v[222:225], v[16:19]
	v_mfma_f32_16x16x32_bf16 v[12:15], v[144:147], v[222:225], v[12:15]
	v_mfma_f32_16x16x32_bf16 v[56:59], v[148:151], v[174:177], v[56:59]
	v_mfma_f32_16x16x32_bf16 v[52:55], v[156:159], v[174:177], v[52:55]
	v_mfma_f32_16x16x32_bf16 v[40:43], v[148:151], v[182:185], v[40:43]
	v_mfma_f32_16x16x32_bf16 v[36:39], v[156:159], v[182:185], v[36:39]
	v_mfma_f32_16x16x32_bf16 v[24:27], v[148:151], v[190:193], v[24:27]
	v_mfma_f32_16x16x32_bf16 v[20:23], v[156:159], v[190:193], v[20:23]
	v_mfma_f32_16x16x32_bf16 v[8:11], v[148:151], v[210:213], v[8:11]
	v_mfma_f32_16x16x32_bf16 v[4:7], v[156:159], v[210:213], v[4:7]
	v_mfma_f32_16x16x32_bf16 v[56:59], v[152:155], v[178:181], v[56:59]
	v_mfma_f32_16x16x32_bf16 v[52:55], v[170:173], v[178:181], v[52:55]
	v_mfma_f32_16x16x32_bf16 v[40:43], v[152:155], v[186:189], v[40:43]
	v_mfma_f32_16x16x32_bf16 v[36:39], v[170:173], v[186:189], v[36:39]
	v_mfma_f32_16x16x32_bf16 v[24:27], v[152:155], v[206:209], v[24:27]
	v_mfma_f32_16x16x32_bf16 v[20:23], v[170:173], v[206:209], v[20:23]
	v_mfma_f32_16x16x32_bf16 v[8:11], v[152:155], v[222:225], v[8:11]
	v_mfma_f32_16x16x32_bf16 v[4:7], v[170:173], v[222:225], v[4:7]
	s_barrier
	s_add_i32 s58, s58, 2
	s_add_u32 s48, s48, 0x80000
	s_addc_u32 s49, s49, 0
	s_add_u32 s28, s28, 0x400000
	s_addc_u32 s29, s29, 0
	s_cmpk_gt_u32 s58, 0x55
	s_cbranch_scc0 .LBB0_433
	s_and_b64 vcc, exec, s[14:15]
	s_cbranch_vccz .LBB0_436
	s_barrier

.LBB0_576:
	s_add_u32 s27, s96, 0x1fc000
	s_addc_u32 s29, s97, 0
	s_and_b64 s[14:15], exec, s[14:15]
	s_cselect_b32 s14, s18, s27
	s_cselect_b32 s15, s7, s29
	s_add_u32 vcc_lo, s14, 0x200000
	s_addc_u32 vcc_hi, s15, 0
	s_add_i32 s27, 0, 0x10000
	s_add_i32 s29, 0, 0x14000
	ds_read_b128 v[162:165], v143
	ds_read_b128 v[166:169], v143 offset:1024
	ds_read_b128 v[172:175], v143 offset:2048
	ds_read_b128 v[176:179], v143 offset:3072
	ds_read_b128 v[180:183], v143 offset:16384
	ds_read_b128 v[184:187], v143 offset:17408
	ds_read_b128 v[188:191], v143 offset:18432
	ds_read_b128 v[192:195], v143 offset:19456
	s_add_i32 m0, s48, 0xc000
	ds_read_b128 v[200:203], v170
	ds_read_b128 v[204:207], v170 offset:1024
	ds_read_b128 v[208:211], v170 offset:2048
	ds_read_b128 v[222:225], v170 offset:3072
	ds_read_b128 v[226:229], v170 offset:4096
	ds_read_b128 v[230:233], v170 offset:5120
	ds_read_b128 v[234:237], v170 offset:6144
	ds_read_b128 v[238:241], v170 offset:7168
	global_load_lds_dwordx4 v158, s[96:97]
	s_add_i32 m0, s48, 0xe000
	s_nop 0
	global_load_lds_dwordx4 v160, s[96:97]
	s_waitcnt vmcnt(8)
	s_waitcnt lgkmcnt(0)
	s_barrier
	v_mfma_f32_16x16x32_bf16 v[128:131], v[162:165], v[200:203], v[128:131]
	v_mfma_f32_16x16x32_bf16 v[124:127], v[172:175], v[200:203], v[124:127]
	v_mfma_f32_16x16x32_bf16 v[112:115], v[162:165], v[208:211], v[112:115]
	v_mfma_f32_16x16x32_bf16 v[108:111], v[172:175], v[208:211], v[108:111]
	v_mfma_f32_16x16x32_bf16 v[96:99], v[162:165], v[226:229], v[96:99]
	v_mfma_f32_16x16x32_bf16 v[92:95], v[172:175], v[226:229], v[92:95]
	v_mfma_f32_16x16x32_bf16 v[80:83], v[162:165], v[234:237], v[80:83]
	v_mfma_f32_16x16x32_bf16 v[76:79], v[172:175], v[234:237], v[76:79]
	v_mfma_f32_16x16x32_bf16 v[128:131], v[166:169], v[204:207], v[128:131]
	v_mfma_f32_16x16x32_bf16 v[124:127], v[176:179], v[204:207], v[124:127]
	v_mfma_f32_16x16x32_bf16 v[112:115], v[166:169], v[222:225], v[112:115]
	v_mfma_f32_16x16x32_bf16 v[108:111], v[176:179], v[222:225], v[108:111]
	v_mfma_f32_16x16x32_bf16 v[96:99], v[166:169], v[230:233], v[96:99]
	v_mfma_f32_16x16x32_bf16 v[92:95], v[176:179], v[230:233], v[92:95]
	v_mfma_f32_16x16x32_bf16 v[80:83], v[166:169], v[238:241], v[80:83]
	v_mfma_f32_16x16x32_bf16 v[76:79], v[176:179], v[238:241], v[76:79]
	v_mfma_f32_16x16x32_bf16 v[120:123], v[180:183], v[200:203], v[120:123]
	v_mfma_f32_16x16x32_bf16 v[116:119], v[188:191], v[200:203], v[116:119]
	v_mfma_f32_16x16x32_bf16 v[104:107], v[180:183], v[208:211], v[104:107]
	v_mfma_f32_16x16x32_bf16 v[100:103], v[188:191], v[208:211], v[100:103]
	v_mfma_f32_16x16x32_bf16 v[88:91], v[180:183], v[226:229], v[88:91]
	v_mfma_f32_16x16x32_bf16 v[84:87], v[188:191], v[226:229], v[84:87]
	v_mfma_f32_16x16x32_bf16 v[72:75], v[180:183], v[234:237], v[72:75]
	v_mfma_f32_16x16x32_bf16 v[68:71], v[188:191], v[234:237], v[68:71]
	v_mfma_f32_16x16x32_bf16 v[120:123], v[184:187], v[204:207], v[120:123]
	v_mfma_f32_16x16x32_bf16 v[116:119], v[192:195], v[204:207], v[116:119]
	v_mfma_f32_16x16x32_bf16 v[104:107], v[184:187], v[222:225], v[104:107]
	v_mfma_f32_16x16x32_bf16 v[100:103], v[192:195], v[222:225], v[100:103]
	v_mfma_f32_16x16x32_bf16 v[88:91], v[184:187], v[230:233], v[88:91]
	v_mfma_f32_16x16x32_bf16 v[84:87], v[192:195], v[230:233], v[84:87]
	v_mfma_f32_16x16x32_bf16 v[72:75], v[184:187], v[238:241], v[72:75]
	v_mfma_f32_16x16x32_bf16 v[68:71], v[192:195], v[238:241], v[68:71]
	s_barrier
	s_add_i32 s27, s27, s90
	s_mov_b32 m0, s27
	ds_read_b128 v[200:203], v170 offset:16384
	ds_read_b128 v[204:207], v170 offset:17408
	ds_read_b128 v[208:211], v170 offset:18432
	ds_read_b128 v[222:225], v170 offset:19456
	ds_read_b128 v[226:229], v170 offset:20480
	ds_read_b128 v[230:233], v170 offset:21504
	ds_read_b128 v[234:237], v170 offset:22528
	ds_read_b128 v[238:241], v170 offset:23552
	global_load_lds_dwordx4 v134, s[72:73]
	s_add_i32 m0, s27, 0x2000
	s_add_u32 s74, s72, 0x4000
	s_addc_u32 s75, s73, 0
	s_add_i32 s27, s29, s90
	global_load_lds_dwordx4 v138, s[72:73]
	s_mov_b32 m0, s27
	s_nop 0
	global_load_lds_dwordx4 v134, s[74:75]
	s_add_i32 m0, s27, 0x2000
	s_nop 0
	global_load_lds_dwordx4 v138, s[74:75]
	s_mov_b32 m0, s48
	s_nop 0
	global_load_lds_dwordx4 v132, s[14:15]
	s_mov_b32 m0, s49
	s_nop 0
	global_load_lds_dwordx4 v136, s[14:15]
	s_waitcnt vmcnt(8)
	s_waitcnt lgkmcnt(0)
	s_barrier
	v_mfma_f32_16x16x32_bf16 v[64:67], v[162:165], v[200:203], v[64:67]
	v_mfma_f32_16x16x32_bf16 v[60:63], v[172:175], v[200:203], v[60:63]
	v_mfma_f32_16x16x32_bf16 v[48:51], v[162:165], v[208:211], v[48:51]
	v_mfma_f32_16x16x32_bf16 v[44:47], v[172:175], v[208:211], v[44:47]
	v_mfma_f32_16x16x32_bf16 v[32:35], v[162:165], v[226:229], v[32:35]
	v_mfma_f32_16x16x32_bf16 v[28:31], v[172:175], v[226:229], v[28:31]
	v_mfma_f32_16x16x32_bf16 v[16:19], v[162:165], v[234:237], v[16:19]
	v_mfma_f32_16x16x32_bf16 v[12:15], v[172:175], v[234:237], v[12:15]
	v_mfma_f32_16x16x32_bf16 v[64:67], v[166:169], v[204:207], v[64:67]
	v_mfma_f32_16x16x32_bf16 v[60:63], v[176:179], v[204:207], v[60:63]
	v_mfma_f32_16x16x32_bf16 v[48:51], v[166:169], v[222:225], v[48:51]
	v_mfma_f32_16x16x32_bf16 v[44:47], v[176:179], v[222:225], v[44:47]
	v_mfma_f32_16x16x32_bf16 v[32:35], v[166:169], v[230:233], v[32:35]
	v_mfma_f32_16x16x32_bf16 v[28:31], v[176:179], v[230:233], v[28:31]
	v_mfma_f32_16x16x32_bf16 v[16:19], v[166:169], v[238:241], v[16:19]
	v_mfma_f32_16x16x32_bf16 v[12:15], v[176:179], v[238:241], v[12:15]
	v_mfma_f32_16x16x32_bf16 v[56:59], v[180:183], v[200:203], v[56:59]
	v_mfma_f32_16x16x32_bf16 v[52:55], v[188:191], v[200:203], v[52:55]
	v_mfma_f32_16x16x32_bf16 v[40:43], v[180:183], v[208:211], v[40:43]
	v_mfma_f32_16x16x32_bf16 v[36:39], v[188:191], v[208:211], v[36:39]
	v_mfma_f32_16x16x32_bf16 v[24:27], v[180:183], v[226:229], v[24:27]
	v_mfma_f32_16x16x32_bf16 v[20:23], v[188:191], v[226:229], v[20:23]
	v_mfma_f32_16x16x32_bf16 v[8:11], v[180:183], v[234:237], v[8:11]
	v_mfma_f32_16x16x32_bf16 v[4:7], v[188:191], v[234:237], v[4:7]
	v_mfma_f32_16x16x32_bf16 v[56:59], v[184:187], v[204:207], v[56:59]
	v_mfma_f32_16x16x32_bf16 v[52:55], v[192:195], v[204:207], v[52:55]
	v_mfma_f32_16x16x32_bf16 v[40:43], v[184:187], v[222:225], v[40:43]
	v_mfma_f32_16x16x32_bf16 v[36:39], v[192:195], v[222:225], v[36:39]
	v_mfma_f32_16x16x32_bf16 v[24:27], v[184:187], v[230:233], v[24:27]
	v_mfma_f32_16x16x32_bf16 v[20:23], v[192:195], v[230:233], v[20:23]
	v_mfma_f32_16x16x32_bf16 v[8:11], v[184:187], v[238:241], v[8:11]
	v_mfma_f32_16x16x32_bf16 v[4:7], v[192:195], v[238:241], v[4:7]
	s_barrier
	s_add_i32 s27, 0, 0x18000
	s_add_i32 s29, 0, 0x1c000
	ds_read_b128 v[162:165], v143 offset:32768
	ds_read_b128 v[166:169], v143 offset:33792
	ds_read_b128 v[172:175], v143 offset:34816
	ds_read_b128 v[176:179], v143 offset:35840
	ds_read_b128 v[180:183], v143 offset:49152
	ds_read_b128 v[184:187], v143 offset:50176
	ds_read_b128 v[188:191], v143 offset:51200
	ds_read_b128 v[192:195], v143 offset:52224
	s_add_u32 s14, s14, 0x4000
	s_addc_u32 s15, s15, 0
	s_mov_b32 m0, s66
	ds_read_b128 v[200:203], v170 offset:32768
	ds_read_b128 v[204:207], v170 offset:33792
	ds_read_b128 v[208:211], v170 offset:34816
	ds_read_b128 v[222:225], v170 offset:35840
	ds_read_b128 v[226:229], v170 offset:36864
	ds_read_b128 v[230:233], v170 offset:37888
	ds_read_b128 v[234:237], v170 offset:38912
	ds_read_b128 v[238:241], v170 offset:39936
	global_load_lds_dwordx4 v132, s[14:15]
	s_mov_b32 m0, s67
	s_nop 0
	global_load_lds_dwordx4 v136, s[14:15]
	s_waitcnt vmcnt(8)
	s_waitcnt lgkmcnt(0)
	s_barrier
	v_mfma_f32_16x16x32_bf16 v[128:131], v[162:165], v[200:203], v[128:131]
	v_mfma_f32_16x16x32_bf16 v[124:127], v[172:175], v[200:203], v[124:127]
	v_mfma_f32_16x16x32_bf16 v[112:115], v[162:165], v[208:211], v[112:115]
	v_mfma_f32_16x16x32_bf16 v[108:111], v[172:175], v[208:211], v[108:111]
	v_mfma_f32_16x16x32_bf16 v[96:99], v[162:165], v[226:229], v[96:99]
	v_mfma_f32_16x16x32_bf16 v[92:95], v[172:175], v[226:229], v[92:95]
	v_mfma_f32_16x16x32_bf16 v[80:83], v[162:165], v[234:237], v[80:83]
	v_mfma_f32_16x16x32_bf16 v[76:79], v[172:175], v[234:237], v[76:79]
	v_mfma_f32_16x16x32_bf16 v[128:131], v[166:169], v[204:207], v[128:131]
	v_mfma_f32_16x16x32_bf16 v[124:127], v[176:179], v[204:207], v[124:127]
	v_mfma_f32_16x16x32_bf16 v[112:115], v[166:169], v[222:225], v[112:115]
	v_mfma_f32_16x16x32_bf16 v[108:111], v[176:179], v[222:225], v[108:111]
	v_mfma_f32_16x16x32_bf16 v[96:99], v[166:169], v[230:233], v[96:99]
	v_mfma_f32_16x16x32_bf16 v[92:95], v[176:179], v[230:233], v[92:95]
	v_mfma_f32_16x16x32_bf16 v[80:83], v[166:169], v[238:241], v[80:83]
	v_mfma_f32_16x16x32_bf16 v[76:79], v[176:179], v[238:241], v[76:79]
	v_mfma_f32_16x16x32_bf16 v[120:123], v[180:183], v[200:203], v[120:123]
	v_mfma_f32_16x16x32_bf16 v[116:119], v[188:191], v[200:203], v[116:119]
	v_mfma_f32_16x16x32_bf16 v[104:107], v[180:183], v[208:211], v[104:107]
	v_mfma_f32_16x16x32_bf16 v[100:103], v[188:191], v[208:211], v[100:103]
	v_mfma_f32_16x16x32_bf16 v[88:91], v[180:183], v[226:229], v[88:91]
	v_mfma_f32_16x16x32_bf16 v[84:87], v[188:191], v[226:229], v[84:87]
	v_mfma_f32_16x16x32_bf16 v[72:75], v[180:183], v[234:237], v[72:75]
	v_mfma_f32_16x16x32_bf16 v[68:71], v[188:191], v[234:237], v[68:71]
	v_mfma_f32_16x16x32_bf16 v[120:123], v[184:187], v[204:207], v[120:123]
	v_mfma_f32_16x16x32_bf16 v[116:119], v[192:195], v[204:207], v[116:119]
	v_mfma_f32_16x16x32_bf16 v[104:107], v[184:187], v[222:225], v[104:107]
	v_mfma_f32_16x16x32_bf16 v[100:103], v[192:195], v[222:225], v[100:103]
	v_mfma_f32_16x16x32_bf16 v[88:91], v[184:187], v[230:233], v[88:91]
	v_mfma_f32_16x16x32_bf16 v[84:87], v[192:195], v[230:233], v[84:87]
	v_mfma_f32_16x16x32_bf16 v[72:75], v[184:187], v[238:241], v[72:75]
	v_mfma_f32_16x16x32_bf16 v[68:71], v[192:195], v[238:241], v[68:71]
	s_barrier
	s_add_u32 s14, s72, 0x70000
	s_addc_u32 s15, s73, 0
	s_add_i32 s27, s27, s90
	s_mov_b32 m0, s27
	ds_read_b128 v[200:203], v170 offset:49152
	ds_read_b128 v[204:207], v170 offset:50176
	ds_read_b128 v[208:211], v170 offset:51200
	ds_read_b128 v[222:225], v170 offset:52224
	ds_read_b128 v[226:229], v170 offset:53248
	ds_read_b128 v[230:233], v170 offset:54272
	ds_read_b128 v[234:237], v170 offset:55296
	ds_read_b128 v[238:241], v170 offset:56320
	global_load_lds_dwordx4 v134, s[14:15]
	s_add_i32 m0, s27, 0x2000
	s_nop 0
	global_load_lds_dwordx4 v138, s[14:15]
	s_add_u32 s14, s72, 0x74000
	s_addc_u32 s15, s73, 0
	s_add_i32 s27, s29, s90
	s_mov_b32 m0, s27
	s_nop 0
	global_load_lds_dwordx4 v134, s[14:15]
	s_add_i32 m0, s27, 0x2000
	s_nop 0
	global_load_lds_dwordx4 v138, s[14:15]
	s_mov_b32 m0, s59
	s_nop 0
	global_load_lds_dwordx4 v132, vcc
	s_mov_b32 m0, s70
	s_nop 0
	global_load_lds_dwordx4 v136, vcc
	s_waitcnt vmcnt(8)
	s_waitcnt lgkmcnt(0)
	s_barrier
	v_mfma_f32_16x16x32_bf16 v[64:67], v[162:165], v[200:203], v[64:67]
	v_mfma_f32_16x16x32_bf16 v[60:63], v[172:175], v[200:203], v[60:63]
	v_mfma_f32_16x16x32_bf16 v[48:51], v[162:165], v[208:211], v[48:51]
	v_mfma_f32_16x16x32_bf16 v[44:47], v[172:175], v[208:211], v[44:47]
	v_mfma_f32_16x16x32_bf16 v[32:35], v[162:165], v[226:229], v[32:35]
	v_mfma_f32_16x16x32_bf16 v[28:31], v[172:175], v[226:229], v[28:31]
	v_mfma_f32_16x16x32_bf16 v[16:19], v[162:165], v[234:237], v[16:19]
	v_mfma_f32_16x16x32_bf16 v[12:15], v[172:175], v[234:237], v[12:15]
	v_mfma_f32_16x16x32_bf16 v[64:67], v[166:169], v[204:207], v[64:67]
	v_mfma_f32_16x16x32_bf16 v[60:63], v[176:179], v[204:207], v[60:63]
	v_mfma_f32_16x16x32_bf16 v[48:51], v[166:169], v[222:225], v[48:51]
	v_mfma_f32_16x16x32_bf16 v[44:47], v[176:179], v[222:225], v[44:47]
	v_mfma_f32_16x16x32_bf16 v[32:35], v[166:169], v[230:233], v[32:35]
	v_mfma_f32_16x16x32_bf16 v[28:31], v[176:179], v[230:233], v[28:31]
	v_mfma_f32_16x16x32_bf16 v[16:19], v[166:169], v[238:241], v[16:19]
	v_mfma_f32_16x16x32_bf16 v[12:15], v[176:179], v[238:241], v[12:15]
	v_mfma_f32_16x16x32_bf16 v[56:59], v[180:183], v[200:203], v[56:59]
	v_mfma_f32_16x16x32_bf16 v[52:55], v[188:191], v[200:203], v[52:55]
	v_mfma_f32_16x16x32_bf16 v[40:43], v[180:183], v[208:211], v[40:43]
	v_mfma_f32_16x16x32_bf16 v[36:39], v[188:191], v[208:211], v[36:39]
	v_mfma_f32_16x16x32_bf16 v[24:27], v[180:183], v[226:229], v[24:27]
	v_mfma_f32_16x16x32_bf16 v[20:23], v[188:191], v[226:229], v[20:23]
	v_mfma_f32_16x16x32_bf16 v[8:11], v[180:183], v[234:237], v[8:11]
	v_mfma_f32_16x16x32_bf16 v[4:7], v[188:191], v[234:237], v[4:7]
	v_mfma_f32_16x16x32_bf16 v[56:59], v[184:187], v[204:207], v[56:59]
	v_mfma_f32_16x16x32_bf16 v[52:55], v[192:195], v[204:207], v[52:55]
	v_mfma_f32_16x16x32_bf16 v[40:43], v[184:187], v[222:225], v[40:43]
	v_mfma_f32_16x16x32_bf16 v[36:39], v[192:195], v[222:225], v[36:39]
	v_mfma_f32_16x16x32_bf16 v[24:27], v[184:187], v[230:233], v[24:27]
	v_mfma_f32_16x16x32_bf16 v[20:23], v[192:195], v[230:233], v[20:23]
	v_mfma_f32_16x16x32_bf16 v[8:11], v[184:187], v[238:241], v[8:11]
	v_mfma_f32_16x16x32_bf16 v[4:7], v[192:195], v[238:241], v[4:7]
	s_barrier
	s_add_i32 s19, s19, 2
	s_add_u32 s94, s94, 0xe0000
	s_addc_u32 s95, s95, 0
	s_add_u32 s96, s96, 0x400000
	s_addc_u32 s97, s97, 0
	s_cmp_gt_u32 s19, 29
	s_cbranch_scc1 .LBB0_579

.LBB0_881:
	s_add_u32 s29, s46, 0x1fc000
	s_addc_u32 s48, s47, 0
	s_and_b64 s[34:35], exec, s[72:73]
	s_cselect_b32 s74, s27, s29
	s_cselect_b32 s75, s21, s48
	s_add_u32 s72, s74, 0x200000
	s_addc_u32 s73, s75, 0
	s_add_i32 s29, 0, 0x10000
	s_add_i32 s48, 0, 0x14000
	ds_read_b128 v[100:103], v222
	ds_read_b128 v[104:107], v222 offset:1024
	ds_read_b128 v[108:111], v222 offset:2048
	ds_read_b128 v[112:115], v222 offset:3072
	ds_read_b128 v[116:119], v222 offset:16384
	ds_read_b128 v[124:127], v222 offset:17408
	ds_read_b128 v[132:135], v222 offset:18432
	ds_read_b128 v[136:139], v222 offset:19456
	s_add_i32 m0, s82, 0xc000
	ds_read_b128 v[140:143], v227
	ds_read_b128 v[144:147], v227 offset:1024
	ds_read_b128 v[156:159], v227 offset:2048
	ds_read_b128 v[160:163], v227 offset:3072
	ds_read_b128 v[164:167], v227 offset:4096
	ds_read_b128 v[172:175], v227 offset:5120
	ds_read_b128 v[180:183], v227 offset:6144
	ds_read_b128 v[184:187], v227 offset:7168
	global_load_lds_dwordx4 v208, s[46:47]
	s_add_i32 m0, s82, 0xe000
	s_nop 0
	global_load_lds_dwordx4 v210, s[46:47]
	s_waitcnt vmcnt(8)
	s_waitcnt lgkmcnt(0)
	s_barrier
	v_mfma_f32_16x16x32_bf16 v[192:195], v[100:103], v[140:143], v[192:195]
	v_mfma_f32_16x16x32_bf16 v[188:191], v[108:111], v[140:143], v[188:191]
	v_mfma_f32_16x16x32_bf16 v[176:179], v[100:103], v[156:159], v[176:179]
	v_mfma_f32_16x16x32_bf16 v[168:171], v[108:111], v[156:159], v[168:171]
	v_mfma_f32_16x16x32_bf16 v[152:155], v[100:103], v[164:167], v[152:155]
	v_mfma_f32_16x16x32_bf16 v[148:151], v[108:111], v[164:167], v[148:151]
	v_mfma_f32_16x16x32_bf16 v[128:131], v[100:103], v[180:183], v[128:131]
	v_mfma_f32_16x16x32_bf16 v[120:123], v[108:111], v[180:183], v[120:123]
	v_mfma_f32_16x16x32_bf16 v[192:195], v[104:107], v[144:147], v[192:195]
	v_mfma_f32_16x16x32_bf16 v[188:191], v[112:115], v[144:147], v[188:191]
	v_mfma_f32_16x16x32_bf16 v[176:179], v[104:107], v[160:163], v[176:179]
	v_mfma_f32_16x16x32_bf16 v[168:171], v[112:115], v[160:163], v[168:171]
	v_mfma_f32_16x16x32_bf16 v[152:155], v[104:107], v[172:175], v[152:155]
	v_mfma_f32_16x16x32_bf16 v[148:151], v[112:115], v[172:175], v[148:151]
	v_mfma_f32_16x16x32_bf16 v[128:131], v[104:107], v[184:187], v[128:131]
	v_mfma_f32_16x16x32_bf16 v[120:123], v[112:115], v[184:187], v[120:123]
	v_mfma_f32_16x16x32_bf16 v[64:67], v[116:119], v[140:143], v[64:67]
	v_mfma_f32_16x16x32_bf16 v[60:63], v[132:135], v[140:143], v[60:63]
	v_mfma_f32_16x16x32_bf16 v[56:59], v[116:119], v[156:159], v[56:59]
	v_mfma_f32_16x16x32_bf16 v[52:55], v[132:135], v[156:159], v[52:55]
	v_mfma_f32_16x16x32_bf16 v[48:51], v[116:119], v[164:167], v[48:51]
	v_mfma_f32_16x16x32_bf16 v[44:47], v[132:135], v[164:167], v[44:47]
	v_mfma_f32_16x16x32_bf16 v[40:43], v[116:119], v[180:183], v[40:43]
	v_mfma_f32_16x16x32_bf16 v[36:39], v[132:135], v[180:183], v[36:39]
	v_mfma_f32_16x16x32_bf16 v[64:67], v[124:127], v[144:147], v[64:67]
	v_mfma_f32_16x16x32_bf16 v[60:63], v[136:139], v[144:147], v[60:63]
	v_mfma_f32_16x16x32_bf16 v[56:59], v[124:127], v[160:163], v[56:59]
	v_mfma_f32_16x16x32_bf16 v[52:55], v[136:139], v[160:163], v[52:55]
	v_mfma_f32_16x16x32_bf16 v[48:51], v[124:127], v[172:175], v[48:51]
	v_mfma_f32_16x16x32_bf16 v[44:47], v[136:139], v[172:175], v[44:47]
	v_mfma_f32_16x16x32_bf16 v[40:43], v[124:127], v[184:187], v[40:43]
	v_mfma_f32_16x16x32_bf16 v[36:39], v[136:139], v[184:187], v[36:39]
	s_barrier
	s_add_i32 s29, s29, s79
	s_mov_b32 m0, s29
	ds_read_b128 v[140:143], v227 offset:16384
	ds_read_b128 v[144:147], v227 offset:17408
	ds_read_b128 v[156:159], v227 offset:18432
	ds_read_b128 v[160:163], v227 offset:19456
	ds_read_b128 v[164:167], v227 offset:20480
	ds_read_b128 v[172:175], v227 offset:21504
	ds_read_b128 v[180:183], v227 offset:22528
	ds_read_b128 v[184:187], v227 offset:23552
	global_load_lds_dwordx4 v202, s[36:37]
	s_add_i32 m0, s29, 0x2000
	s_add_u32 s34, s36, 0x4000
	s_addc_u32 s35, s37, 0
	s_add_i32 s29, s48, s79
	global_load_lds_dwordx4 v206, s[36:37]
	s_mov_b32 m0, s29
	s_nop 0
	global_load_lds_dwordx4 v202, s[34:35]
	s_add_i32 m0, s29, 0x2000
	s_nop 0
	global_load_lds_dwordx4 v206, s[34:35]
	s_mov_b32 m0, s82
	s_nop 0
	global_load_lds_dwordx4 v200, s[74:75]
	s_mov_b32 m0, s83
	s_nop 0
	global_load_lds_dwordx4 v204, s[74:75]
	s_waitcnt vmcnt(8)
	s_waitcnt lgkmcnt(0)
	s_barrier
	v_mfma_f32_16x16x32_bf16 v[96:99], v[100:103], v[140:143], v[96:99]
	v_mfma_f32_16x16x32_bf16 v[92:95], v[108:111], v[140:143], v[92:95]
	v_mfma_f32_16x16x32_bf16 v[88:91], v[100:103], v[156:159], v[88:91]
	v_mfma_f32_16x16x32_bf16 v[84:87], v[108:111], v[156:159], v[84:87]
	v_mfma_f32_16x16x32_bf16 v[80:83], v[100:103], v[164:167], v[80:83]
	v_mfma_f32_16x16x32_bf16 v[76:79], v[108:111], v[164:167], v[76:79]
	v_mfma_f32_16x16x32_bf16 v[72:75], v[100:103], v[180:183], v[72:75]
	v_mfma_f32_16x16x32_bf16 v[68:71], v[108:111], v[180:183], v[68:71]
	v_mfma_f32_16x16x32_bf16 v[96:99], v[104:107], v[144:147], v[96:99]
	v_mfma_f32_16x16x32_bf16 v[92:95], v[112:115], v[144:147], v[92:95]
	v_mfma_f32_16x16x32_bf16 v[88:91], v[104:107], v[160:163], v[88:91]
	v_mfma_f32_16x16x32_bf16 v[84:87], v[112:115], v[160:163], v[84:87]
	v_mfma_f32_16x16x32_bf16 v[80:83], v[104:107], v[172:175], v[80:83]
	v_mfma_f32_16x16x32_bf16 v[76:79], v[112:115], v[172:175], v[76:79]
	v_mfma_f32_16x16x32_bf16 v[72:75], v[104:107], v[184:187], v[72:75]
	v_mfma_f32_16x16x32_bf16 v[68:71], v[112:115], v[184:187], v[68:71]
	v_mfma_f32_16x16x32_bf16 v[32:35], v[116:119], v[140:143], v[32:35]
	v_mfma_f32_16x16x32_bf16 v[28:31], v[132:135], v[140:143], v[28:31]
	v_mfma_f32_16x16x32_bf16 v[24:27], v[116:119], v[156:159], v[24:27]
	v_mfma_f32_16x16x32_bf16 v[20:23], v[132:135], v[156:159], v[20:23]
	v_mfma_f32_16x16x32_bf16 v[16:19], v[116:119], v[164:167], v[16:19]
	v_mfma_f32_16x16x32_bf16 v[12:15], v[132:135], v[164:167], v[12:15]
	v_mfma_f32_16x16x32_bf16 v[8:11], v[116:119], v[180:183], v[8:11]
	v_mfma_f32_16x16x32_bf16 v[4:7], v[132:135], v[180:183], v[4:7]
	v_mfma_f32_16x16x32_bf16 v[32:35], v[124:127], v[144:147], v[32:35]
	v_mfma_f32_16x16x32_bf16 v[28:31], v[136:139], v[144:147], v[28:31]
	v_mfma_f32_16x16x32_bf16 v[24:27], v[124:127], v[160:163], v[24:27]
	v_mfma_f32_16x16x32_bf16 v[20:23], v[136:139], v[160:163], v[20:23]
	v_mfma_f32_16x16x32_bf16 v[16:19], v[124:127], v[172:175], v[16:19]
	v_mfma_f32_16x16x32_bf16 v[12:15], v[136:139], v[172:175], v[12:15]
	v_mfma_f32_16x16x32_bf16 v[8:11], v[124:127], v[184:187], v[8:11]
	v_mfma_f32_16x16x32_bf16 v[4:7], v[136:139], v[184:187], v[4:7]
	s_barrier
	s_add_i32 s29, 0, 0x18000
	s_add_i32 s48, 0, 0x1c000
	ds_read_b128 v[100:103], v222 offset:32768
	ds_read_b128 v[104:107], v222 offset:33792
	ds_read_b128 v[108:111], v222 offset:34816
	ds_read_b128 v[112:115], v222 offset:35840
	ds_read_b128 v[116:119], v222 offset:49152
	ds_read_b128 v[124:127], v222 offset:50176
	ds_read_b128 v[132:135], v222 offset:51200
	ds_read_b128 v[136:139], v222 offset:52224
	s_add_u32 s34, s74, 0x4000
	s_addc_u32 s35, s75, 0
	s_mov_b32 m0, s86
	ds_read_b128 v[140:143], v227 offset:32768
	ds_read_b128 v[144:147], v227 offset:33792
	ds_read_b128 v[156:159], v227 offset:34816
	ds_read_b128 v[160:163], v227 offset:35840
	ds_read_b128 v[164:167], v227 offset:36864
	ds_read_b128 v[172:175], v227 offset:37888
	ds_read_b128 v[180:183], v227 offset:38912
	ds_read_b128 v[184:187], v227 offset:39936
	global_load_lds_dwordx4 v200, s[34:35]
	s_mov_b32 m0, s87
	s_nop 0
	global_load_lds_dwordx4 v204, s[34:35]
	s_waitcnt vmcnt(8)
	s_waitcnt lgkmcnt(0)
	s_barrier
	v_mfma_f32_16x16x32_bf16 v[192:195], v[100:103], v[140:143], v[192:195]
	v_mfma_f32_16x16x32_bf16 v[188:191], v[108:111], v[140:143], v[188:191]
	v_mfma_f32_16x16x32_bf16 v[176:179], v[100:103], v[156:159], v[176:179]
	v_mfma_f32_16x16x32_bf16 v[168:171], v[108:111], v[156:159], v[168:171]
	v_mfma_f32_16x16x32_bf16 v[152:155], v[100:103], v[164:167], v[152:155]
	v_mfma_f32_16x16x32_bf16 v[148:151], v[108:111], v[164:167], v[148:151]
	v_mfma_f32_16x16x32_bf16 v[128:131], v[100:103], v[180:183], v[128:131]
	v_mfma_f32_16x16x32_bf16 v[120:123], v[108:111], v[180:183], v[120:123]
	v_mfma_f32_16x16x32_bf16 v[192:195], v[104:107], v[144:147], v[192:195]
	v_mfma_f32_16x16x32_bf16 v[188:191], v[112:115], v[144:147], v[188:191]
	v_mfma_f32_16x16x32_bf16 v[176:179], v[104:107], v[160:163], v[176:179]
	v_mfma_f32_16x16x32_bf16 v[168:171], v[112:115], v[160:163], v[168:171]
	v_mfma_f32_16x16x32_bf16 v[152:155], v[104:107], v[172:175], v[152:155]
	v_mfma_f32_16x16x32_bf16 v[148:151], v[112:115], v[172:175], v[148:151]
	v_mfma_f32_16x16x32_bf16 v[128:131], v[104:107], v[184:187], v[128:131]
	v_mfma_f32_16x16x32_bf16 v[120:123], v[112:115], v[184:187], v[120:123]
	v_mfma_f32_16x16x32_bf16 v[64:67], v[116:119], v[140:143], v[64:67]
	v_mfma_f32_16x16x32_bf16 v[60:63], v[132:135], v[140:143], v[60:63]
	v_mfma_f32_16x16x32_bf16 v[56:59], v[116:119], v[156:159], v[56:59]
	v_mfma_f32_16x16x32_bf16 v[52:55], v[132:135], v[156:159], v[52:55]
	v_mfma_f32_16x16x32_bf16 v[48:51], v[116:119], v[164:167], v[48:51]
	v_mfma_f32_16x16x32_bf16 v[44:47], v[132:135], v[164:167], v[44:47]
	v_mfma_f32_16x16x32_bf16 v[40:43], v[116:119], v[180:183], v[40:43]
	v_mfma_f32_16x16x32_bf16 v[36:39], v[132:135], v[180:183], v[36:39]
	v_mfma_f32_16x16x32_bf16 v[64:67], v[124:127], v[144:147], v[64:67]
	v_mfma_f32_16x16x32_bf16 v[60:63], v[136:139], v[144:147], v[60:63]
	v_mfma_f32_16x16x32_bf16 v[56:59], v[124:127], v[160:163], v[56:59]
	v_mfma_f32_16x16x32_bf16 v[52:55], v[136:139], v[160:163], v[52:55]
	v_mfma_f32_16x16x32_bf16 v[48:51], v[124:127], v[172:175], v[48:51]
	v_mfma_f32_16x16x32_bf16 v[44:47], v[136:139], v[172:175], v[44:47]
	v_mfma_f32_16x16x32_bf16 v[40:43], v[124:127], v[184:187], v[40:43]
	v_mfma_f32_16x16x32_bf16 v[36:39], v[136:139], v[184:187], v[36:39]
	s_barrier
	s_add_u32 s34, s36, 0x30000
	s_addc_u32 s35, s37, 0
	s_add_i32 s29, s29, s79
	s_mov_b32 m0, s29
	ds_read_b128 v[140:143], v227 offset:49152
	ds_read_b128 v[144:147], v227 offset:50176
	ds_read_b128 v[156:159], v227 offset:51200
	ds_read_b128 v[160:163], v227 offset:52224
	ds_read_b128 v[164:167], v227 offset:53248
	ds_read_b128 v[172:175], v227 offset:54272
	ds_read_b128 v[180:183], v227 offset:55296
	ds_read_b128 v[184:187], v227 offset:56320
	global_load_lds_dwordx4 v202, s[34:35]
	s_add_i32 m0, s29, 0x2000
	s_nop 0
	global_load_lds_dwordx4 v206, s[34:35]
	s_add_u32 s34, s36, 0x34000
	s_addc_u32 s35, s37, 0
	s_add_i32 s29, s48, s79
	s_mov_b32 m0, s29
	s_nop 0
	global_load_lds_dwordx4 v202, s[34:35]
	s_add_i32 m0, s29, 0x2000
	s_nop 0
	global_load_lds_dwordx4 v206, s[34:35]
	s_mov_b32 m0, s94
	s_nop 0
	global_load_lds_dwordx4 v200, s[72:73]
	s_mov_b32 m0, s95
	s_nop 0
	global_load_lds_dwordx4 v204, s[72:73]
	s_waitcnt vmcnt(8)
	s_waitcnt lgkmcnt(0)
	s_barrier
	v_mfma_f32_16x16x32_bf16 v[96:99], v[100:103], v[140:143], v[96:99]
	v_mfma_f32_16x16x32_bf16 v[92:95], v[108:111], v[140:143], v[92:95]
	v_mfma_f32_16x16x32_bf16 v[88:91], v[100:103], v[156:159], v[88:91]
	v_mfma_f32_16x16x32_bf16 v[84:87], v[108:111], v[156:159], v[84:87]
	v_mfma_f32_16x16x32_bf16 v[80:83], v[100:103], v[164:167], v[80:83]
	v_mfma_f32_16x16x32_bf16 v[76:79], v[108:111], v[164:167], v[76:79]
	v_mfma_f32_16x16x32_bf16 v[72:75], v[100:103], v[180:183], v[72:75]
	v_mfma_f32_16x16x32_bf16 v[68:71], v[108:111], v[180:183], v[68:71]
	v_mfma_f32_16x16x32_bf16 v[96:99], v[104:107], v[144:147], v[96:99]
	v_mfma_f32_16x16x32_bf16 v[92:95], v[112:115], v[144:147], v[92:95]
	v_mfma_f32_16x16x32_bf16 v[88:91], v[104:107], v[160:163], v[88:91]
	v_mfma_f32_16x16x32_bf16 v[84:87], v[112:115], v[160:163], v[84:87]
	v_mfma_f32_16x16x32_bf16 v[80:83], v[104:107], v[172:175], v[80:83]
	v_mfma_f32_16x16x32_bf16 v[76:79], v[112:115], v[172:175], v[76:79]
	v_mfma_f32_16x16x32_bf16 v[72:75], v[104:107], v[184:187], v[72:75]
	v_mfma_f32_16x16x32_bf16 v[68:71], v[112:115], v[184:187], v[68:71]
	v_mfma_f32_16x16x32_bf16 v[32:35], v[116:119], v[140:143], v[32:35]
	v_mfma_f32_16x16x32_bf16 v[28:31], v[132:135], v[140:143], v[28:31]
	v_mfma_f32_16x16x32_bf16 v[24:27], v[116:119], v[156:159], v[24:27]
	v_mfma_f32_16x16x32_bf16 v[20:23], v[132:135], v[156:159], v[20:23]
	v_mfma_f32_16x16x32_bf16 v[16:19], v[116:119], v[164:167], v[16:19]
	v_mfma_f32_16x16x32_bf16 v[12:15], v[132:135], v[164:167], v[12:15]
	v_mfma_f32_16x16x32_bf16 v[8:11], v[116:119], v[180:183], v[8:11]
	v_mfma_f32_16x16x32_bf16 v[4:7], v[132:135], v[180:183], v[4:7]
	v_mfma_f32_16x16x32_bf16 v[32:35], v[124:127], v[144:147], v[32:35]
	v_mfma_f32_16x16x32_bf16 v[28:31], v[136:139], v[144:147], v[28:31]
	v_mfma_f32_16x16x32_bf16 v[24:27], v[124:127], v[160:163], v[24:27]
	v_mfma_f32_16x16x32_bf16 v[20:23], v[136:139], v[160:163], v[20:23]
	v_mfma_f32_16x16x32_bf16 v[16:19], v[124:127], v[172:175], v[16:19]
	v_mfma_f32_16x16x32_bf16 v[12:15], v[136:139], v[172:175], v[12:15]
	v_mfma_f32_16x16x32_bf16 v[8:11], v[124:127], v[184:187], v[8:11]
	v_mfma_f32_16x16x32_bf16 v[4:7], v[136:139], v[184:187], v[4:7]
	s_barrier
	s_add_i32 s19, s19, 2
	s_add_u32 s44, s44, 0x60000
	s_addc_u32 s45, s45, 0
	s_add_u32 s46, s46, 0x400000
	s_addc_u32 s47, s47, 0
	s_cmp_gt_u32 s19, 5
	s_cbranch_scc1 .LBB0_884

.LBB0_936:
	s_or_b32 s83, s82, 1
	s_mul_hi_u32 s86, s83, 0x280000
	s_mul_i32 s83, s83, 0x280000
	s_add_u32 s83, s46, s83
	s_addc_u32 s86, s47, s86
	s_add_u32 s76, s44, s76
	s_addc_u32 s77, s45, s77
	s_and_b64 s[74:75], exec, s[74:75]
	s_cselect_b32 s97, s23, s77
	s_cselect_b32 s96, s25, s76
	s_add_u32 s94, s36, 0x280000
	s_addc_u32 s95, s37, 0
	s_add_i32 s76, 0, 0x10000
	s_add_i32 s77, 0, 0x14000
	ds_read_b128 v[142:145], v140
	ds_read_b128 v[146:149], v140 offset:1024
	ds_read_b128 v[150:153], v140 offset:2048
	ds_read_b128 v[154:157], v140 offset:3072
	ds_read_b128 v[158:161], v140 offset:16384
	ds_read_b128 v[162:165], v140 offset:17408
	ds_read_b128 v[166:169], v140 offset:18432
	ds_read_b128 v[170:173], v140 offset:19456
	s_add_u32 s74, s83, 0x4000
	s_addc_u32 s75, s86, 0
	s_add_i32 m0, s31, 0xc000
	ds_read_b128 v[174:177], v141
	ds_read_b128 v[178:181], v141 offset:1024
	ds_read_b128 v[182:185], v141 offset:2048
	ds_read_b128 v[186:189], v141 offset:3072
	ds_read_b128 v[190:193], v141 offset:4096
	ds_read_b128 v[200:203], v141 offset:5120
	ds_read_b128 v[204:207], v141 offset:6144
	ds_read_b128 v[208:211], v141 offset:7168
	global_load_lds_dwordx4 v136, s[74:75]
	s_add_i32 m0, s31, 0xe000
	s_nop 0
	global_load_lds_dwordx4 v134, s[74:75]
	s_waitcnt vmcnt(8)
	s_waitcnt lgkmcnt(0)
	s_barrier
	v_mfma_f32_16x16x32_bf16 v[128:131], v[142:145], v[174:177], v[128:131]
	v_mfma_f32_16x16x32_bf16 v[124:127], v[150:153], v[174:177], v[124:127]
	v_mfma_f32_16x16x32_bf16 v[120:123], v[142:145], v[182:185], v[120:123]
	v_mfma_f32_16x16x32_bf16 v[112:115], v[150:153], v[182:185], v[112:115]
	v_mfma_f32_16x16x32_bf16 v[104:107], v[142:145], v[190:193], v[104:107]
	v_mfma_f32_16x16x32_bf16 v[96:99], v[150:153], v[190:193], v[96:99]
	v_mfma_f32_16x16x32_bf16 v[88:91], v[142:145], v[204:207], v[88:91]
	v_mfma_f32_16x16x32_bf16 v[80:83], v[150:153], v[204:207], v[80:83]
	v_mfma_f32_16x16x32_bf16 v[128:131], v[146:149], v[178:181], v[128:131]
	v_mfma_f32_16x16x32_bf16 v[124:127], v[154:157], v[178:181], v[124:127]
	v_mfma_f32_16x16x32_bf16 v[120:123], v[146:149], v[186:189], v[120:123]
	v_mfma_f32_16x16x32_bf16 v[112:115], v[154:157], v[186:189], v[112:115]
	v_mfma_f32_16x16x32_bf16 v[104:107], v[146:149], v[200:203], v[104:107]
	v_mfma_f32_16x16x32_bf16 v[96:99], v[154:157], v[200:203], v[96:99]
	v_mfma_f32_16x16x32_bf16 v[88:91], v[146:149], v[208:211], v[88:91]
	v_mfma_f32_16x16x32_bf16 v[80:83], v[154:157], v[208:211], v[80:83]
	v_mfma_f32_16x16x32_bf16 v[116:119], v[158:161], v[174:177], v[116:119]
	v_mfma_f32_16x16x32_bf16 v[108:111], v[166:169], v[174:177], v[108:111]
	v_mfma_f32_16x16x32_bf16 v[100:103], v[158:161], v[182:185], v[100:103]
	v_mfma_f32_16x16x32_bf16 v[92:95], v[166:169], v[182:185], v[92:95]
	v_mfma_f32_16x16x32_bf16 v[84:87], v[158:161], v[190:193], v[84:87]
	v_mfma_f32_16x16x32_bf16 v[76:79], v[166:169], v[190:193], v[76:79]
	v_mfma_f32_16x16x32_bf16 v[72:75], v[158:161], v[204:207], v[72:75]
	v_mfma_f32_16x16x32_bf16 v[68:71], v[166:169], v[204:207], v[68:71]
	v_mfma_f32_16x16x32_bf16 v[116:119], v[162:165], v[178:181], v[116:119]
	v_mfma_f32_16x16x32_bf16 v[108:111], v[170:173], v[178:181], v[108:111]
	v_mfma_f32_16x16x32_bf16 v[100:103], v[162:165], v[186:189], v[100:103]
	v_mfma_f32_16x16x32_bf16 v[92:95], v[170:173], v[186:189], v[92:95]
	v_mfma_f32_16x16x32_bf16 v[84:87], v[162:165], v[200:203], v[84:87]
	v_mfma_f32_16x16x32_bf16 v[76:79], v[170:173], v[200:203], v[76:79]
	v_mfma_f32_16x16x32_bf16 v[72:75], v[162:165], v[208:211], v[72:75]
	v_mfma_f32_16x16x32_bf16 v[68:71], v[170:173], v[208:211], v[68:71]
	s_barrier
	s_add_i32 s74, s76, s58
	s_mov_b32 m0, s74
	ds_read_b128 v[174:177], v141 offset:16384
	ds_read_b128 v[178:181], v141 offset:17408
	ds_read_b128 v[182:185], v141 offset:18432
	ds_read_b128 v[186:189], v141 offset:19456
	ds_read_b128 v[190:193], v141 offset:20480
	ds_read_b128 v[200:203], v141 offset:21504
	ds_read_b128 v[204:207], v141 offset:22528
	ds_read_b128 v[208:211], v141 offset:23552
	global_load_lds_dwordx4 v2, s[96:97]
	s_add_i32 m0, s74, 0x2000
	s_add_u32 s74, s96, 0x4000
	s_addc_u32 s75, s97, 0
	s_add_i32 s76, s77, s58
	global_load_lds_dwordx4 v132, s[96:97]
	s_mov_b32 m0, s76
	s_nop 0
	global_load_lds_dwordx4 v2, s[74:75]
	s_add_i32 m0, s76, 0x2000
	s_nop 0
	global_load_lds_dwordx4 v132, s[74:75]
	s_mov_b32 m0, s31
	s_nop 0
	global_load_lds_dwordx4 v136, s[36:37]
	s_mov_b32 m0, s61
	s_nop 0
	global_load_lds_dwordx4 v134, s[36:37]
	s_waitcnt vmcnt(8)
	s_waitcnt lgkmcnt(0)
	s_barrier
	v_mfma_f32_16x16x32_bf16 v[64:67], v[142:145], v[174:177], v[64:67]
	v_mfma_f32_16x16x32_bf16 v[60:63], v[150:153], v[174:177], v[60:63]
	v_mfma_f32_16x16x32_bf16 v[56:59], v[142:145], v[182:185], v[56:59]
	v_mfma_f32_16x16x32_bf16 v[48:51], v[150:153], v[182:185], v[48:51]
	v_mfma_f32_16x16x32_bf16 v[40:43], v[142:145], v[190:193], v[40:43]
	v_mfma_f32_16x16x32_bf16 v[32:35], v[150:153], v[190:193], v[32:35]
	v_mfma_f32_16x16x32_bf16 v[24:27], v[142:145], v[204:207], v[24:27]
	v_mfma_f32_16x16x32_bf16 v[16:19], v[150:153], v[204:207], v[16:19]
	v_mfma_f32_16x16x32_bf16 v[64:67], v[146:149], v[178:181], v[64:67]
	v_mfma_f32_16x16x32_bf16 v[60:63], v[154:157], v[178:181], v[60:63]
	v_mfma_f32_16x16x32_bf16 v[56:59], v[146:149], v[186:189], v[56:59]
	v_mfma_f32_16x16x32_bf16 v[48:51], v[154:157], v[186:189], v[48:51]
	v_mfma_f32_16x16x32_bf16 v[40:43], v[146:149], v[200:203], v[40:43]
	v_mfma_f32_16x16x32_bf16 v[32:35], v[154:157], v[200:203], v[32:35]
	v_mfma_f32_16x16x32_bf16 v[24:27], v[146:149], v[208:211], v[24:27]
	v_mfma_f32_16x16x32_bf16 v[16:19], v[154:157], v[208:211], v[16:19]
	v_mfma_f32_16x16x32_bf16 v[52:55], v[158:161], v[174:177], v[52:55]
	v_mfma_f32_16x16x32_bf16 v[44:47], v[166:169], v[174:177], v[44:47]
	v_mfma_f32_16x16x32_bf16 v[36:39], v[158:161], v[182:185], v[36:39]
	v_mfma_f32_16x16x32_bf16 v[28:31], v[166:169], v[182:185], v[28:31]
	v_mfma_f32_16x16x32_bf16 v[20:23], v[158:161], v[190:193], v[20:23]
	v_mfma_f32_16x16x32_bf16 v[12:15], v[166:169], v[190:193], v[12:15]
	v_mfma_f32_16x16x32_bf16 v[8:11], v[158:161], v[204:207], v[8:11]
	v_mfma_f32_16x16x32_bf16 v[4:7], v[166:169], v[204:207], v[4:7]
	v_mfma_f32_16x16x32_bf16 v[52:55], v[162:165], v[178:181], v[52:55]
	v_mfma_f32_16x16x32_bf16 v[44:47], v[170:173], v[178:181], v[44:47]
	v_mfma_f32_16x16x32_bf16 v[36:39], v[162:165], v[186:189], v[36:39]
	v_mfma_f32_16x16x32_bf16 v[28:31], v[170:173], v[186:189], v[28:31]
	v_mfma_f32_16x16x32_bf16 v[20:23], v[162:165], v[200:203], v[20:23]
	v_mfma_f32_16x16x32_bf16 v[12:15], v[170:173], v[200:203], v[12:15]
	v_mfma_f32_16x16x32_bf16 v[8:11], v[162:165], v[208:211], v[8:11]
	v_mfma_f32_16x16x32_bf16 v[4:7], v[170:173], v[208:211], v[4:7]
	s_barrier
	s_add_i32 s74, 0, 0x18000
	s_add_i32 s75, 0, 0x1c000
	ds_read_b128 v[142:145], v140 offset:32768
	ds_read_b128 v[146:149], v140 offset:33792
	ds_read_b128 v[150:153], v140 offset:34816
	ds_read_b128 v[154:157], v140 offset:35840
	ds_read_b128 v[158:161], v140 offset:49152
	ds_read_b128 v[162:165], v140 offset:50176
	ds_read_b128 v[166:169], v140 offset:51200
	ds_read_b128 v[170:173], v140 offset:52224
	s_add_u32 s36, s36, 0x4000
	s_addc_u32 s37, s37, 0
	s_mov_b32 m0, s66
	ds_read_b128 v[174:177], v141 offset:32768
	ds_read_b128 v[178:181], v141 offset:33792
	ds_read_b128 v[182:185], v141 offset:34816
	ds_read_b128 v[186:189], v141 offset:35840
	ds_read_b128 v[190:193], v141 offset:36864
	ds_read_b128 v[200:203], v141 offset:37888
	ds_read_b128 v[204:207], v141 offset:38912
	ds_read_b128 v[208:211], v141 offset:39936
	global_load_lds_dwordx4 v136, s[36:37]
	s_mov_b32 m0, s67
	s_nop 0
	global_load_lds_dwordx4 v134, s[36:37]
	s_waitcnt vmcnt(8)
	s_waitcnt lgkmcnt(0)
	s_barrier
	v_mfma_f32_16x16x32_bf16 v[128:131], v[142:145], v[174:177], v[128:131]
	v_mfma_f32_16x16x32_bf16 v[124:127], v[150:153], v[174:177], v[124:127]
	v_mfma_f32_16x16x32_bf16 v[120:123], v[142:145], v[182:185], v[120:123]
	v_mfma_f32_16x16x32_bf16 v[112:115], v[150:153], v[182:185], v[112:115]
	v_mfma_f32_16x16x32_bf16 v[104:107], v[142:145], v[190:193], v[104:107]
	v_mfma_f32_16x16x32_bf16 v[96:99], v[150:153], v[190:193], v[96:99]
	v_mfma_f32_16x16x32_bf16 v[88:91], v[142:145], v[204:207], v[88:91]
	v_mfma_f32_16x16x32_bf16 v[80:83], v[150:153], v[204:207], v[80:83]
	v_mfma_f32_16x16x32_bf16 v[128:131], v[146:149], v[178:181], v[128:131]
	v_mfma_f32_16x16x32_bf16 v[124:127], v[154:157], v[178:181], v[124:127]
	v_mfma_f32_16x16x32_bf16 v[120:123], v[146:149], v[186:189], v[120:123]
	v_mfma_f32_16x16x32_bf16 v[112:115], v[154:157], v[186:189], v[112:115]
	v_mfma_f32_16x16x32_bf16 v[104:107], v[146:149], v[200:203], v[104:107]
	v_mfma_f32_16x16x32_bf16 v[96:99], v[154:157], v[200:203], v[96:99]
	v_mfma_f32_16x16x32_bf16 v[88:91], v[146:149], v[208:211], v[88:91]
	v_mfma_f32_16x16x32_bf16 v[80:83], v[154:157], v[208:211], v[80:83]
	v_mfma_f32_16x16x32_bf16 v[116:119], v[158:161], v[174:177], v[116:119]
	v_mfma_f32_16x16x32_bf16 v[108:111], v[166:169], v[174:177], v[108:111]
	v_mfma_f32_16x16x32_bf16 v[100:103], v[158:161], v[182:185], v[100:103]
	v_mfma_f32_16x16x32_bf16 v[92:95], v[166:169], v[182:185], v[92:95]
	v_mfma_f32_16x16x32_bf16 v[84:87], v[158:161], v[190:193], v[84:87]
	v_mfma_f32_16x16x32_bf16 v[76:79], v[166:169], v[190:193], v[76:79]
	v_mfma_f32_16x16x32_bf16 v[72:75], v[158:161], v[204:207], v[72:75]
	v_mfma_f32_16x16x32_bf16 v[68:71], v[166:169], v[204:207], v[68:71]
	v_mfma_f32_16x16x32_bf16 v[116:119], v[162:165], v[178:181], v[116:119]
	v_mfma_f32_16x16x32_bf16 v[108:111], v[170:173], v[178:181], v[108:111]
	v_mfma_f32_16x16x32_bf16 v[100:103], v[162:165], v[186:189], v[100:103]
	v_mfma_f32_16x16x32_bf16 v[92:95], v[170:173], v[186:189], v[92:95]
	v_mfma_f32_16x16x32_bf16 v[84:87], v[162:165], v[200:203], v[84:87]
	v_mfma_f32_16x16x32_bf16 v[76:79], v[170:173], v[200:203], v[76:79]
	v_mfma_f32_16x16x32_bf16 v[72:75], v[162:165], v[208:211], v[72:75]
	v_mfma_f32_16x16x32_bf16 v[68:71], v[170:173], v[208:211], v[68:71]
	s_barrier
	s_add_u32 s36, s96, 0x40000
	s_addc_u32 s37, s97, 0
	s_add_i32 s74, s74, s58
	s_mov_b32 m0, s74
	ds_read_b128 v[174:177], v141 offset:49152
	ds_read_b128 v[178:181], v141 offset:50176
	ds_read_b128 v[182:185], v141 offset:51200
	ds_read_b128 v[186:189], v141 offset:52224
	ds_read_b128 v[190:193], v141 offset:53248
	ds_read_b128 v[200:203], v141 offset:54272
	ds_read_b128 v[204:207], v141 offset:55296
	ds_read_b128 v[208:211], v141 offset:56320
	global_load_lds_dwordx4 v2, s[36:37]
	s_add_i32 m0, s74, 0x2000
	s_nop 0
	global_load_lds_dwordx4 v132, s[36:37]
	s_add_u32 s36, s96, 0x44000
	s_addc_u32 s37, s97, 0
	s_add_i32 s74, s75, s58
	s_mov_b32 m0, s74
	s_nop 0
	global_load_lds_dwordx4 v2, s[36:37]
	s_add_i32 m0, s74, 0x2000
	s_nop 0
	global_load_lds_dwordx4 v132, s[36:37]
	s_mov_b32 m0, s70
	s_nop 0
	global_load_lds_dwordx4 v136, s[94:95]
	s_mov_b32 m0, s71
	s_nop 0
	global_load_lds_dwordx4 v134, s[94:95]
	s_waitcnt vmcnt(8)
	s_waitcnt lgkmcnt(0)
	s_barrier
	v_mfma_f32_16x16x32_bf16 v[64:67], v[142:145], v[174:177], v[64:67]
	v_mfma_f32_16x16x32_bf16 v[60:63], v[150:153], v[174:177], v[60:63]
	v_mfma_f32_16x16x32_bf16 v[56:59], v[142:145], v[182:185], v[56:59]
	v_mfma_f32_16x16x32_bf16 v[48:51], v[150:153], v[182:185], v[48:51]
	v_mfma_f32_16x16x32_bf16 v[40:43], v[142:145], v[190:193], v[40:43]
	v_mfma_f32_16x16x32_bf16 v[32:35], v[150:153], v[190:193], v[32:35]
	v_mfma_f32_16x16x32_bf16 v[24:27], v[142:145], v[204:207], v[24:27]
	v_mfma_f32_16x16x32_bf16 v[16:19], v[150:153], v[204:207], v[16:19]
	v_mfma_f32_16x16x32_bf16 v[64:67], v[146:149], v[178:181], v[64:67]
	v_mfma_f32_16x16x32_bf16 v[60:63], v[154:157], v[178:181], v[60:63]
	v_mfma_f32_16x16x32_bf16 v[56:59], v[146:149], v[186:189], v[56:59]
	v_mfma_f32_16x16x32_bf16 v[48:51], v[154:157], v[186:189], v[48:51]
	v_mfma_f32_16x16x32_bf16 v[40:43], v[146:149], v[200:203], v[40:43]
	v_mfma_f32_16x16x32_bf16 v[32:35], v[154:157], v[200:203], v[32:35]
	v_mfma_f32_16x16x32_bf16 v[24:27], v[146:149], v[208:211], v[24:27]
	v_mfma_f32_16x16x32_bf16 v[16:19], v[154:157], v[208:211], v[16:19]
	v_mfma_f32_16x16x32_bf16 v[52:55], v[158:161], v[174:177], v[52:55]
	v_mfma_f32_16x16x32_bf16 v[44:47], v[166:169], v[174:177], v[44:47]
	v_mfma_f32_16x16x32_bf16 v[36:39], v[158:161], v[182:185], v[36:39]
	v_mfma_f32_16x16x32_bf16 v[28:31], v[166:169], v[182:185], v[28:31]
	v_mfma_f32_16x16x32_bf16 v[20:23], v[158:161], v[190:193], v[20:23]
	v_mfma_f32_16x16x32_bf16 v[12:15], v[166:169], v[190:193], v[12:15]
	v_mfma_f32_16x16x32_bf16 v[8:11], v[158:161], v[204:207], v[8:11]
	v_mfma_f32_16x16x32_bf16 v[4:7], v[166:169], v[204:207], v[4:7]
	v_mfma_f32_16x16x32_bf16 v[52:55], v[162:165], v[178:181], v[52:55]
	v_mfma_f32_16x16x32_bf16 v[44:47], v[170:173], v[178:181], v[44:47]
	v_mfma_f32_16x16x32_bf16 v[36:39], v[162:165], v[186:189], v[36:39]
	v_mfma_f32_16x16x32_bf16 v[28:31], v[170:173], v[186:189], v[28:31]
	v_mfma_f32_16x16x32_bf16 v[20:23], v[162:165], v[200:203], v[20:23]
	v_mfma_f32_16x16x32_bf16 v[12:15], v[170:173], v[200:203], v[12:15]
	v_mfma_f32_16x16x32_bf16 v[8:11], v[162:165], v[208:211], v[8:11]
	v_mfma_f32_16x16x32_bf16 v[4:7], v[170:173], v[208:211], v[4:7]
	s_barrier
	s_cmp_lg_u32 s82, 0
	s_mov_b32 s82, s40
	s_cbranch_scc1 .LBB0_939

.LBB0_1211:
	s_add_u32 s28, s26, 0x1fc000
	s_addc_u32 s29, s27, 0
	s_cmp_eq_u32 s58, 28
	s_cselect_b32 s36, s34, s28
	s_cselect_b32 s37, s19, s29
	s_cselect_b32 s31, s15, s49
	s_cselect_b32 s30, s35, s48
	s_add_u32 s28, s36, 0x200000
	s_addc_u32 s29, s37, 0
	s_add_i32 s59, 0, 0x10000
	s_add_i32 s61, 0, 0x14000
	ds_read_b128 v[68:71], v191
	ds_read_b128 v[72:75], v191 offset:1024
	ds_read_b128 v[76:79], v191 offset:2048
	ds_read_b128 v[80:83], v191 offset:3072
	ds_read_b128 v[148:151], v191 offset:16384
	ds_read_b128 v[152:155], v191 offset:17408
	ds_read_b128 v[156:159], v191 offset:18432
	ds_read_b128 v[160:163], v191 offset:19456
	s_add_i32 m0, s73, 0xc000
	ds_read_b128 v[164:167], v193
	ds_read_b128 v[178:181], v193 offset:1024
	ds_read_b128 v[182:185], v193 offset:2048
	ds_read_b128 v[186:189], v193 offset:3072
	ds_read_b128 v[200:203], v193 offset:4096
	ds_read_b128 v[204:207], v193 offset:5120
	ds_read_b128 v[208:211], v193 offset:6144
	ds_read_b128 v[222:225], v193 offset:7168
	global_load_lds_dwordx4 v174, s[26:27]
	s_add_i32 m0, s73, 0xe000
	s_nop 0
	global_load_lds_dwordx4 v176, s[26:27]
	s_waitcnt vmcnt(8)
	s_waitcnt lgkmcnt(0)
	s_barrier
	v_mfma_f32_16x16x32_bf16 v[144:147], v[68:71], v[164:167], v[144:147]
	v_mfma_f32_16x16x32_bf16 v[140:143], v[76:79], v[164:167], v[140:143]
	v_mfma_f32_16x16x32_bf16 v[136:139], v[68:71], v[182:185], v[136:139]
	v_mfma_f32_16x16x32_bf16 v[128:131], v[76:79], v[182:185], v[128:131]
	v_mfma_f32_16x16x32_bf16 v[112:115], v[68:71], v[200:203], v[112:115]
	v_mfma_f32_16x16x32_bf16 v[108:111], v[76:79], v[200:203], v[108:111]
	v_mfma_f32_16x16x32_bf16 v[104:107], v[68:71], v[208:211], v[104:107]
	v_mfma_f32_16x16x32_bf16 v[96:99], v[76:79], v[208:211], v[96:99]
	v_mfma_f32_16x16x32_bf16 v[144:147], v[72:75], v[178:181], v[144:147]
	v_mfma_f32_16x16x32_bf16 v[140:143], v[80:83], v[178:181], v[140:143]
	v_mfma_f32_16x16x32_bf16 v[136:139], v[72:75], v[186:189], v[136:139]
	v_mfma_f32_16x16x32_bf16 v[128:131], v[80:83], v[186:189], v[128:131]
	v_mfma_f32_16x16x32_bf16 v[112:115], v[72:75], v[204:207], v[112:115]
	v_mfma_f32_16x16x32_bf16 v[108:111], v[80:83], v[204:207], v[108:111]
	v_mfma_f32_16x16x32_bf16 v[104:107], v[72:75], v[222:225], v[104:107]
	v_mfma_f32_16x16x32_bf16 v[96:99], v[80:83], v[222:225], v[96:99]
	v_mfma_f32_16x16x32_bf16 v[132:135], v[148:151], v[164:167], v[132:135]
	v_mfma_f32_16x16x32_bf16 v[124:127], v[156:159], v[164:167], v[124:127]
	v_mfma_f32_16x16x32_bf16 v[120:123], v[148:151], v[182:185], v[120:123]
	v_mfma_f32_16x16x32_bf16 v[116:119], v[156:159], v[182:185], v[116:119]
	v_mfma_f32_16x16x32_bf16 v[100:103], v[148:151], v[200:203], v[100:103]
	v_mfma_f32_16x16x32_bf16 v[92:95], v[156:159], v[200:203], v[92:95]
	v_mfma_f32_16x16x32_bf16 v[88:91], v[148:151], v[208:211], v[88:91]
	v_mfma_f32_16x16x32_bf16 v[84:87], v[156:159], v[208:211], v[84:87]
	v_mfma_f32_16x16x32_bf16 v[132:135], v[152:155], v[178:181], v[132:135]
	v_mfma_f32_16x16x32_bf16 v[124:127], v[160:163], v[178:181], v[124:127]
	v_mfma_f32_16x16x32_bf16 v[120:123], v[152:155], v[186:189], v[120:123]
	v_mfma_f32_16x16x32_bf16 v[116:119], v[160:163], v[186:189], v[116:119]
	v_mfma_f32_16x16x32_bf16 v[100:103], v[152:155], v[204:207], v[100:103]
	v_mfma_f32_16x16x32_bf16 v[92:95], v[160:163], v[204:207], v[92:95]
	v_mfma_f32_16x16x32_bf16 v[88:91], v[152:155], v[222:225], v[88:91]
	v_mfma_f32_16x16x32_bf16 v[84:87], v[160:163], v[222:225], v[84:87]
	s_barrier
	s_add_i32 s59, s59, s72
	s_mov_b32 m0, s59
	ds_read_b128 v[164:167], v193 offset:16384
	ds_read_b128 v[178:181], v193 offset:17408
	ds_read_b128 v[182:185], v193 offset:18432
	ds_read_b128 v[186:189], v193 offset:19456
	ds_read_b128 v[200:203], v193 offset:20480
	ds_read_b128 v[204:207], v193 offset:21504
	ds_read_b128 v[208:211], v193 offset:22528
	ds_read_b128 v[222:225], v193 offset:23552
	global_load_lds_dwordx4 v2, s[30:31]
	s_add_i32 m0, s59, 0x2000
	s_add_u32 s66, s30, 0x4000
	s_addc_u32 s67, s31, 0
	s_add_i32 s59, s61, s72
	global_load_lds_dwordx4 v172, s[30:31]
	s_mov_b32 m0, s59
	s_nop 0
	global_load_lds_dwordx4 v2, s[66:67]
	s_add_i32 m0, s59, 0x2000
	s_nop 0
	global_load_lds_dwordx4 v172, s[66:67]
	s_mov_b32 m0, s73
	s_nop 0
	global_load_lds_dwordx4 v168, s[36:37]
	s_mov_b32 m0, s74
	s_nop 0
	global_load_lds_dwordx4 v170, s[36:37]
	s_waitcnt vmcnt(8)
	s_waitcnt lgkmcnt(0)
	s_barrier
	v_mfma_f32_16x16x32_bf16 v[64:67], v[68:71], v[164:167], v[64:67]
	v_mfma_f32_16x16x32_bf16 v[60:63], v[76:79], v[164:167], v[60:63]
	v_mfma_f32_16x16x32_bf16 v[48:51], v[68:71], v[182:185], v[48:51]
	v_mfma_f32_16x16x32_bf16 v[44:47], v[76:79], v[182:185], v[44:47]
	v_mfma_f32_16x16x32_bf16 v[32:35], v[68:71], v[200:203], v[32:35]
	v_mfma_f32_16x16x32_bf16 v[28:31], v[76:79], v[200:203], v[28:31]
	v_mfma_f32_16x16x32_bf16 v[16:19], v[68:71], v[208:211], v[16:19]
	v_mfma_f32_16x16x32_bf16 v[12:15], v[76:79], v[208:211], v[12:15]
	v_mfma_f32_16x16x32_bf16 v[64:67], v[72:75], v[178:181], v[64:67]
	v_mfma_f32_16x16x32_bf16 v[60:63], v[80:83], v[178:181], v[60:63]
	v_mfma_f32_16x16x32_bf16 v[48:51], v[72:75], v[186:189], v[48:51]
	v_mfma_f32_16x16x32_bf16 v[44:47], v[80:83], v[186:189], v[44:47]
	v_mfma_f32_16x16x32_bf16 v[32:35], v[72:75], v[204:207], v[32:35]
	v_mfma_f32_16x16x32_bf16 v[28:31], v[80:83], v[204:207], v[28:31]
	v_mfma_f32_16x16x32_bf16 v[16:19], v[72:75], v[222:225], v[16:19]
	v_mfma_f32_16x16x32_bf16 v[12:15], v[80:83], v[222:225], v[12:15]
	v_mfma_f32_16x16x32_bf16 v[56:59], v[148:151], v[164:167], v[56:59]
	v_mfma_f32_16x16x32_bf16 v[52:55], v[156:159], v[164:167], v[52:55]
	v_mfma_f32_16x16x32_bf16 v[40:43], v[148:151], v[182:185], v[40:43]
	v_mfma_f32_16x16x32_bf16 v[36:39], v[156:159], v[182:185], v[36:39]
	v_mfma_f32_16x16x32_bf16 v[24:27], v[148:151], v[200:203], v[24:27]
	v_mfma_f32_16x16x32_bf16 v[20:23], v[156:159], v[200:203], v[20:23]
	v_mfma_f32_16x16x32_bf16 v[8:11], v[148:151], v[208:211], v[8:11]
	v_mfma_f32_16x16x32_bf16 v[4:7], v[156:159], v[208:211], v[4:7]
	v_mfma_f32_16x16x32_bf16 v[56:59], v[152:155], v[178:181], v[56:59]
	v_mfma_f32_16x16x32_bf16 v[52:55], v[160:163], v[178:181], v[52:55]
	v_mfma_f32_16x16x32_bf16 v[40:43], v[152:155], v[186:189], v[40:43]
	v_mfma_f32_16x16x32_bf16 v[36:39], v[160:163], v[186:189], v[36:39]
	v_mfma_f32_16x16x32_bf16 v[24:27], v[152:155], v[204:207], v[24:27]
	v_mfma_f32_16x16x32_bf16 v[20:23], v[160:163], v[204:207], v[20:23]
	v_mfma_f32_16x16x32_bf16 v[8:11], v[152:155], v[222:225], v[8:11]
	v_mfma_f32_16x16x32_bf16 v[4:7], v[160:163], v[222:225], v[4:7]
	s_barrier
	s_add_i32 s59, 0, 0x18000
	s_add_i32 s61, 0, 0x1c000
	ds_read_b128 v[68:71], v191 offset:32768
	ds_read_b128 v[72:75], v191 offset:33792
	ds_read_b128 v[76:79], v191 offset:34816
	ds_read_b128 v[80:83], v191 offset:35840
	ds_read_b128 v[148:151], v191 offset:49152
	ds_read_b128 v[152:155], v191 offset:50176
	ds_read_b128 v[156:159], v191 offset:51200
	ds_read_b128 v[160:163], v191 offset:52224
	s_add_u32 s36, s36, 0x4000
	s_addc_u32 s37, s37, 0
	s_mov_b32 m0, s75
	ds_read_b128 v[164:167], v193 offset:32768
	ds_read_b128 v[178:181], v193 offset:33792
	ds_read_b128 v[182:185], v193 offset:34816
	ds_read_b128 v[186:189], v193 offset:35840
	ds_read_b128 v[200:203], v193 offset:36864
	ds_read_b128 v[204:207], v193 offset:37888
	ds_read_b128 v[208:211], v193 offset:38912
	ds_read_b128 v[222:225], v193 offset:39936
	global_load_lds_dwordx4 v168, s[36:37]
	s_mov_b32 m0, s76
	s_nop 0
	global_load_lds_dwordx4 v170, s[36:37]
	s_waitcnt vmcnt(8)
	s_waitcnt lgkmcnt(0)
	s_barrier
	v_mfma_f32_16x16x32_bf16 v[144:147], v[68:71], v[164:167], v[144:147]
	v_mfma_f32_16x16x32_bf16 v[140:143], v[76:79], v[164:167], v[140:143]
	v_mfma_f32_16x16x32_bf16 v[136:139], v[68:71], v[182:185], v[136:139]
	v_mfma_f32_16x16x32_bf16 v[128:131], v[76:79], v[182:185], v[128:131]
	v_mfma_f32_16x16x32_bf16 v[112:115], v[68:71], v[200:203], v[112:115]
	v_mfma_f32_16x16x32_bf16 v[108:111], v[76:79], v[200:203], v[108:111]
	v_mfma_f32_16x16x32_bf16 v[104:107], v[68:71], v[208:211], v[104:107]
	v_mfma_f32_16x16x32_bf16 v[96:99], v[76:79], v[208:211], v[96:99]
	v_mfma_f32_16x16x32_bf16 v[144:147], v[72:75], v[178:181], v[144:147]
	v_mfma_f32_16x16x32_bf16 v[140:143], v[80:83], v[178:181], v[140:143]
	v_mfma_f32_16x16x32_bf16 v[136:139], v[72:75], v[186:189], v[136:139]
	v_mfma_f32_16x16x32_bf16 v[128:131], v[80:83], v[186:189], v[128:131]
	v_mfma_f32_16x16x32_bf16 v[112:115], v[72:75], v[204:207], v[112:115]
	v_mfma_f32_16x16x32_bf16 v[108:111], v[80:83], v[204:207], v[108:111]
	v_mfma_f32_16x16x32_bf16 v[104:107], v[72:75], v[222:225], v[104:107]
	v_mfma_f32_16x16x32_bf16 v[96:99], v[80:83], v[222:225], v[96:99]
	v_mfma_f32_16x16x32_bf16 v[132:135], v[148:151], v[164:167], v[132:135]
	v_mfma_f32_16x16x32_bf16 v[124:127], v[156:159], v[164:167], v[124:127]
	v_mfma_f32_16x16x32_bf16 v[120:123], v[148:151], v[182:185], v[120:123]
	v_mfma_f32_16x16x32_bf16 v[116:119], v[156:159], v[182:185], v[116:119]
	v_mfma_f32_16x16x32_bf16 v[100:103], v[148:151], v[200:203], v[100:103]
	v_mfma_f32_16x16x32_bf16 v[92:95], v[156:159], v[200:203], v[92:95]
	v_mfma_f32_16x16x32_bf16 v[88:91], v[148:151], v[208:211], v[88:91]
	v_mfma_f32_16x16x32_bf16 v[84:87], v[156:159], v[208:211], v[84:87]
	v_mfma_f32_16x16x32_bf16 v[132:135], v[152:155], v[178:181], v[132:135]
	v_mfma_f32_16x16x32_bf16 v[124:127], v[160:163], v[178:181], v[124:127]
	v_mfma_f32_16x16x32_bf16 v[120:123], v[152:155], v[186:189], v[120:123]
	v_mfma_f32_16x16x32_bf16 v[116:119], v[160:163], v[186:189], v[116:119]
	v_mfma_f32_16x16x32_bf16 v[100:103], v[152:155], v[204:207], v[100:103]
	v_mfma_f32_16x16x32_bf16 v[92:95], v[160:163], v[204:207], v[92:95]
	v_mfma_f32_16x16x32_bf16 v[88:91], v[152:155], v[222:225], v[88:91]
	v_mfma_f32_16x16x32_bf16 v[84:87], v[160:163], v[222:225], v[84:87]
	s_barrier
	s_add_u32 s36, s30, 0x40000
	s_addc_u32 s37, s31, 0
	s_add_i32 s59, s59, s72
	s_mov_b32 m0, s59
	ds_read_b128 v[164:167], v193 offset:49152
	ds_read_b128 v[178:181], v193 offset:50176
	ds_read_b128 v[182:185], v193 offset:51200
	ds_read_b128 v[186:189], v193 offset:52224
	ds_read_b128 v[200:203], v193 offset:53248
	ds_read_b128 v[204:207], v193 offset:54272
	ds_read_b128 v[208:211], v193 offset:55296
	ds_read_b128 v[222:225], v193 offset:56320
	global_load_lds_dwordx4 v2, s[36:37]
	s_add_i32 m0, s59, 0x2000
	s_add_u32 s30, s30, 0x44000
	s_addc_u32 s31, s31, 0
	global_load_lds_dwordx4 v172, s[36:37]
	s_add_i32 s36, s61, s72
	s_mov_b32 m0, s36
	s_nop 0
	global_load_lds_dwordx4 v2, s[30:31]
	s_add_i32 m0, s36, 0x2000
	s_nop 0
	global_load_lds_dwordx4 v172, s[30:31]
	s_mov_b32 m0, s79
	s_nop 0
	global_load_lds_dwordx4 v168, s[28:29]
	s_mov_b32 m0, s82
	s_nop 0
	global_load_lds_dwordx4 v170, s[28:29]
	s_waitcnt vmcnt(8)
	s_waitcnt lgkmcnt(0)
	s_barrier
	v_mfma_f32_16x16x32_bf16 v[64:67], v[68:71], v[164:167], v[64:67]
	v_mfma_f32_16x16x32_bf16 v[60:63], v[76:79], v[164:167], v[60:63]
	v_mfma_f32_16x16x32_bf16 v[48:51], v[68:71], v[182:185], v[48:51]
	v_mfma_f32_16x16x32_bf16 v[44:47], v[76:79], v[182:185], v[44:47]
	v_mfma_f32_16x16x32_bf16 v[32:35], v[68:71], v[200:203], v[32:35]
	v_mfma_f32_16x16x32_bf16 v[28:31], v[76:79], v[200:203], v[28:31]
	v_mfma_f32_16x16x32_bf16 v[16:19], v[68:71], v[208:211], v[16:19]
	v_mfma_f32_16x16x32_bf16 v[12:15], v[76:79], v[208:211], v[12:15]
	v_mfma_f32_16x16x32_bf16 v[64:67], v[72:75], v[178:181], v[64:67]
	v_mfma_f32_16x16x32_bf16 v[60:63], v[80:83], v[178:181], v[60:63]
	v_mfma_f32_16x16x32_bf16 v[48:51], v[72:75], v[186:189], v[48:51]
	v_mfma_f32_16x16x32_bf16 v[44:47], v[80:83], v[186:189], v[44:47]
	v_mfma_f32_16x16x32_bf16 v[32:35], v[72:75], v[204:207], v[32:35]
	v_mfma_f32_16x16x32_bf16 v[28:31], v[80:83], v[204:207], v[28:31]
	v_mfma_f32_16x16x32_bf16 v[16:19], v[72:75], v[222:225], v[16:19]
	v_mfma_f32_16x16x32_bf16 v[12:15], v[80:83], v[222:225], v[12:15]
	v_mfma_f32_16x16x32_bf16 v[56:59], v[148:151], v[164:167], v[56:59]
	v_mfma_f32_16x16x32_bf16 v[52:55], v[156:159], v[164:167], v[52:55]
	v_mfma_f32_16x16x32_bf16 v[40:43], v[148:151], v[182:185], v[40:43]
	v_mfma_f32_16x16x32_bf16 v[36:39], v[156:159], v[182:185], v[36:39]
	v_mfma_f32_16x16x32_bf16 v[24:27], v[148:151], v[200:203], v[24:27]
	v_mfma_f32_16x16x32_bf16 v[20:23], v[156:159], v[200:203], v[20:23]
	v_mfma_f32_16x16x32_bf16 v[8:11], v[148:151], v[208:211], v[8:11]
	v_mfma_f32_16x16x32_bf16 v[4:7], v[156:159], v[208:211], v[4:7]
	v_mfma_f32_16x16x32_bf16 v[56:59], v[152:155], v[178:181], v[56:59]
	v_mfma_f32_16x16x32_bf16 v[52:55], v[160:163], v[178:181], v[52:55]
	v_mfma_f32_16x16x32_bf16 v[40:43], v[152:155], v[186:189], v[40:43]
	v_mfma_f32_16x16x32_bf16 v[36:39], v[160:163], v[186:189], v[36:39]
	v_mfma_f32_16x16x32_bf16 v[24:27], v[152:155], v[204:207], v[24:27]
	v_mfma_f32_16x16x32_bf16 v[20:23], v[160:163], v[204:207], v[20:23]
	v_mfma_f32_16x16x32_bf16 v[8:11], v[152:155], v[222:225], v[8:11]
	v_mfma_f32_16x16x32_bf16 v[4:7], v[160:163], v[222:225], v[4:7]
	s_barrier
	s_add_i32 s58, s58, 2
	s_add_u32 s48, s48, 0x80000
	s_addc_u32 s49, s49, 0
	s_add_u32 s26, s26, 0x400000
	s_addc_u32 s27, s27, 0
	s_cmp_gt_u32 s58, 29
	s_cbranch_scc0 .LBB0_1211
	s_and_b64 vcc, exec, s[10:11]
	s_cbranch_vccz .LBB0_1214
	s_barrier
